# v013 plus rope epilogue (heads of 64): table entries loaded once per row group into spare VGPRs, the second column-half step no longer reloads them nor waits on the preceding stores
# speedup vs baseline: 1.0020x; 1.0020x over previous
; __device__ __forceinline__ unsigned pk2e(float lo, float hi) { typedef float v2f __attribute__((ext_vector_type(2))); typedef __bf16 v2b __attribute__((ext_vector_type(2))); v2f v = {lo, hi}; v2b b = __builtin_convertvector(v, v2b); return __builtin_bit_cast(unsigned, b); }
;     __device__ __forceinline__ void operator()(const f32x4 (&acc)[2][2][4][2], const Unit& u, int wr, int wc, int fr_, int fq_) const {
;         int ln_ = threadIdx.x & 63; asm volatile("" : "+v"(ln_)); const int fr = ln_ & 15, fq = ln_ >> 4; (void)fr_; (void)fq_;
;         typedef unsigned u32x2v __attribute__((ext_vector_type(2)));
;         int colt = u.pn * BM; bf16_t* base = O0; int ld = ld0; float sc = qscale;
;         const int gcolt = colt;
;         if (split_col && colt >= split_col) { base = O1; ld = ld1; colt -= split_col; sc = 1.f; }
; #pragma unroll
;         for (int ai = 0; ai < 2; ++ai)
; #pragma unroll
;             for (int m = 0; m < 4; ++m) {
;                 const int row = u.pm * BM + ai * HALF + wr * 64 + m * 16 + fr;
;                 const bool lat = row < tlat; const int s = row & 4095, prow = s >> 6, pcol = s & 63;
;                 bf16_t* rowp = base + (size_t)row * ld + colt + wc * 32 + 4 * fq;
; #pragma unroll
;                 for (int bj = 0; bj < 2; ++bj) {
;                     if (MODE == 0) {
;                         const int pos = (wc & 1) ? pcol : prow;
;                         const f32x4* tp = (const f32x4*)(tab + (size_t)(pos * 16 + 4 * fq) * 2);
;                         const f32x4 t0 = tp[0], t1 = tp[1];
;                         const f32x4 x1 = acc[ai][bj][m][0], x2 = acc[ai][bj][m][1];
;                         const float cs[4] = {t0[0], t0[2], t1[0], t1[2]}, sn[4] = {t0[1], t0[3], t1[1], t1[3]};
;                         float o1[4], o2[4];
; #pragma unroll
;                         for (int e = 0; e < 4; ++e) { o1[e] = lat ? x1[e] * cs[e] - x2[e] * sn[e] : x1[e]; o2[e] = lat ? x2[e] * cs[e] + x1[e] * sn[e] : x2[e]; o1[e] *= sc; o2[e] *= sc; }
;                         u32x2v w1, w2; w1.x = pk2e(o1[0], o1[1]); w1.y = pk2e(o1[2], o1[3]); w2.x = pk2e(o2[0], o2[1]); w2.y = pk2e(o2[2], o2[3]);
;                         *(u32x2v*)(rowp + bj * HALF) = w1; *(u32x2v*)(rowp + bj * HALF + 16) = w2;
.LBB0_740:
	s_lshl_b32 s2, s0, 8
	s_add_i32 s3, s2, 0xfffffc00
	s_cmp_lt_i32 s0, 4
	s_cselect_b64 vcc, -1, 0
	s_and_b64 s[0:1], vcc, exec
	s_mov_b32 s0, 0xca00000
	s_cselect_b32 s1, s0, 0x10e00000
	s_cselect_b32 s0, s2, s3
	s_add_u32 s2, s6, s1
	s_addc_u32 s3, s7, 0
	s_ashr_i32 s1, s0, 31
	v_mov_b32_e32 v130, v220
	s_lshl_b64 s[0:1], s[0:1], 1
	s_add_u32 s0, s2, s0
	v_and_b32_e32 v151, 15, v130
	s_addc_u32 s1, s3, s1
	v_ashrrev_i32_e32 v130, 2, v130
	s_add_u32 s0, s0, s91
	v_and_b32_e32 v140, -4, v130
	s_addc_u32 s1, s1, 0
	v_ashrrev_i32_e32 v141, 31, v140
	v_lshl_add_u64 v[142:143], v[140:141], 1, s[0:1]
	s_lshl_b32 s0, s26, 8
	s_add_i32 s0, s0, s79
	v_or_b32_e32 v130, s0, v151
	s_bfe_u32 s1, s0, 0x60006
	v_ashrrev_i32_e32 v131, 31, v130
	v_cndmask_b32_e32 v150, 1.0, v232, vcc
	v_cmp_gt_i32_e32 vcc, s80, v130
	v_lshlrev_b64 v[130:131], 11, v[130:131]
	v_mov_b32_e32 v141, s1
	v_lshl_add_u64 v[144:145], v[142:143], 0, v[130:131]
	v_cndmask_b32_e64 v130, v151, v141, s[4:5]
	v_lshl_add_u32 v130, v130, 4, v140
	v_ashrrev_i32_e32 v131, 31, v130
	v_lshl_add_u64 v[146:147], v[130:131], 3, s[6:7]
	global_load_dwordx4 v[130:133], v[146:147], off offset:16
	global_load_dwordx4 v[152:155], v[146:147], off
	global_load_dwordx4 v[164:167], v[146:147], off offset:16
	global_load_dwordx4 v[168:171], v[146:147], off
	v_mov_b32_e32 v156, v126
	v_mov_b32_e32 v157, v122
	s_mov_b64 s[26:27], -1
	s_waitcnt vmcnt(0)
	v_pk_mul_f32 v[156:157], v[156:157], v[152:153]
	s_nop 0
	v_sub_f32_e32 v156, v156, v157
	v_cndmask_b32_e32 v158, v126, v156, vcc
	v_mov_b32_e32 v156, v122
	v_mov_b32_e32 v157, v126
	v_pk_mul_f32 v[152:153], v[156:157], v[152:153]
	v_mul_f32_e32 v156, v150, v158
	v_add_f32_e32 v126, v153, v152
	v_cndmask_b32_e32 v122, v122, v126, vcc
	v_mul_f32_e32 v157, v150, v122
	v_mov_b32_e32 v122, v127
	v_pk_mul_f32 v[152:153], v[122:123], v[154:155]
	v_mov_b32_e32 v126, v123
	v_sub_f32_e32 v122, v152, v153
	v_cndmask_b32_e32 v122, v127, v122, vcc
	v_pk_mul_f32 v[126:127], v[126:127], v[154:155]
	s_nop 0
	v_add_f32_e32 v126, v127, v126
	v_cndmask_b32_e32 v123, v123, v126, vcc
	v_mul_f32_e32 v126, v150, v122
	v_mul_f32_e32 v127, v150, v123
	v_mov_b32_e32 v122, v128
	v_mov_b32_e32 v123, v124
	v_pk_mul_f32 v[122:123], v[122:123], v[130:131]
	s_nop 0
	v_sub_f32_e32 v122, v122, v123
	v_cndmask_b32_e32 v152, v128, v122, vcc
	v_mov_b32_e32 v122, v124
	v_mov_b32_e32 v123, v128
	v_pk_mul_f32 v[122:123], v[122:123], v[130:131]
	v_mov_b32_e32 v128, v125
	v_add_f32_e32 v122, v123, v122
	v_cndmask_b32_e32 v122, v124, v122, vcc
	v_mov_b32_e32 v124, v129
	v_mul_f32_e32 v131, v150, v122
	v_pk_mul_f32 v[122:123], v[124:125], v[132:133]
	v_mul_f32_e32 v130, v150, v152
	v_sub_f32_e32 v122, v122, v123
	v_cndmask_b32_e32 v124, v129, v122, vcc
	v_pk_mul_f32 v[122:123], v[128:129], v[132:133]
	s_nop 0
	v_add_f32_e32 v122, v123, v122
	v_cndmask_b32_e32 v122, v125, v122, vcc
	v_mul_f32_e32 v123, v150, v124
	v_mul_f32_e32 v125, v150, v122
	v_cvt_pk_bf16_f32 v122, v156, v126
	v_cvt_pk_bf16_f32 v123, v130, v123
	v_cvt_pk_bf16_f32 v124, v157, v127
	v_cvt_pk_bf16_f32 v125, v131, v125
	global_store_dwordx2 v[144:145], v[122:123], off
	global_store_dwordx2 v[144:145], v[124:125], off offset:32
	v_mov_b32_e32 v122, v164
	v_mov_b32_e32 v123, v165
	v_mov_b32_e32 v124, v166
	v_mov_b32_e32 v125, v167
	v_mov_b32_e32 v126, v168
	v_mov_b32_e32 v127, v169
	v_mov_b32_e32 v128, v170
	v_mov_b32_e32 v129, v171
	v_mov_b32_e32 v130, v118
	v_mov_b32_e32 v131, v114
	v_pk_mul_f32 v[130:131], v[130:131], v[126:127]
	s_nop 0
	v_sub_f32_e32 v130, v130, v131
	v_cndmask_b32_e32 v132, v118, v130, vcc
	v_mov_b32_e32 v130, v114
	v_mov_b32_e32 v131, v118
	v_pk_mul_f32 v[126:127], v[130:131], v[126:127]
	v_mul_f32_e32 v130, v150, v132
	v_add_f32_e32 v118, v127, v126
	v_cndmask_b32_e32 v114, v114, v118, vcc
	v_mul_f32_e32 v131, v150, v114
	v_mov_b32_e32 v114, v119
	v_pk_mul_f32 v[126:127], v[114:115], v[128:129]
	v_mov_b32_e32 v118, v115
	v_sub_f32_e32 v114, v126, v127
	v_cndmask_b32_e32 v114, v119, v114, vcc
	v_pk_mul_f32 v[118:119], v[118:119], v[128:129]
	v_mov_b32_e32 v128, v108
	v_add_f32_e32 v118, v119, v118
	v_cndmask_b32_e32 v115, v115, v118, vcc
	v_mul_f32_e32 v118, v150, v114
	v_mul_f32_e32 v119, v150, v115
	v_mov_b32_e32 v114, v120
	v_mov_b32_e32 v115, v116
	v_pk_mul_f32 v[114:115], v[114:115], v[122:123]
	v_mov_b32_e32 v129, v104
	v_sub_f32_e32 v114, v114, v115
	v_cndmask_b32_e32 v126, v120, v114, vcc
	v_mov_b32_e32 v114, v116
	v_mov_b32_e32 v115, v120
	v_pk_mul_f32 v[114:115], v[114:115], v[122:123]
	v_mov_b32_e32 v120, v117
	v_add_f32_e32 v114, v115, v114
	v_cndmask_b32_e32 v114, v116, v114, vcc
	v_mov_b32_e32 v116, v121
	v_mul_f32_e32 v123, v150, v114
	v_pk_mul_f32 v[114:115], v[116:117], v[124:125]
	v_mul_f32_e32 v122, v150, v126
	v_sub_f32_e32 v114, v114, v115
	v_cndmask_b32_e32 v116, v121, v114, vcc
	v_pk_mul_f32 v[114:115], v[120:121], v[124:125]
	s_nop 0
	v_add_f32_e32 v114, v115, v114
	v_cndmask_b32_e32 v114, v117, v114, vcc
	v_mul_f32_e32 v115, v150, v116
	v_mul_f32_e32 v117, v150, v114
	v_cvt_pk_bf16_f32 v114, v130, v118
	v_cvt_pk_bf16_f32 v115, v122, v115
	v_or_b32_e32 v122, 16, v151
	v_cvt_pk_bf16_f32 v116, v131, v119
	v_cvt_pk_bf16_f32 v117, v123, v117
	global_store_dwordx2 v[144:145], v[114:115], off offset:256
	global_store_dwordx2 v[144:145], v[116:117], off offset:288
	v_or_b32_e32 v114, s0, v122
	v_ashrrev_i32_e32 v115, 31, v114
	v_cmp_gt_i32_e32 vcc, s80, v114
	v_lshlrev_b64 v[114:115], 11, v[114:115]
	v_lshl_add_u64 v[118:119], v[142:143], 0, v[114:115]
	v_cndmask_b32_e64 v114, v122, v141, s[4:5]
	v_lshl_add_u32 v114, v114, 4, v140
	v_ashrrev_i32_e32 v115, 31, v114
	v_lshl_add_u64 v[120:121], v[114:115], 3, s[6:7]
	global_load_dwordx4 v[114:117], v[120:121], off offset:16
	global_load_dwordx4 v[124:127], v[120:121], off
	global_load_dwordx4 v[164:167], v[120:121], off offset:16
	global_load_dwordx4 v[168:171], v[120:121], off
	s_waitcnt vmcnt(0)
; __device__ __forceinline__ unsigned pk2e(float lo, float hi) { typedef float v2f __attribute__((ext_vector_type(2))); typedef __bf16 v2b __attribute__((ext_vector_type(2))); v2f v = {lo, hi}; v2b b = __builtin_convertvector(v, v2b); return __builtin_bit_cast(unsigned, b); }
;     __device__ __forceinline__ void operator()(const f32x4 (&acc)[2][2][4][2], const Unit& u, int wr, int wc, int fr_, int fq_) const {
;     ...
; #pragma unroll
;         for (int ai = 0; ai < 2; ++ai)
; #pragma unroll
;             for (int m = 0; m < 4; ++m) {
;                 const int row = u.pm * BM + ai * HALF + wr * 64 + m * 16 + fr;
;                 const bool lat = row < tlat; const int s = row & 4095, prow = s >> 6, pcol = s & 63;
;                 bf16_t* rowp = base + (size_t)row * ld + colt + wc * 32 + 4 * fq;
; #pragma unroll
;                 for (int bj = 0; bj < 2; ++bj) {
;                     if (MODE == 0) {
;                         const int pos = (wc & 1) ? pcol : prow;
;                         const f32x4* tp = (const f32x4*)(tab + (size_t)(pos * 16 + 4 * fq) * 2);
;                         const f32x4 t0 = tp[0], t1 = tp[1];
;                         const f32x4 x1 = acc[ai][bj][m][0], x2 = acc[ai][bj][m][1];
;                         const float cs[4] = {t0[0], t0[2], t1[0], t1[2]}, sn[4] = {t0[1], t0[3], t1[1], t1[3]};
;                         float o1[4], o2[4];
; #pragma unroll
;                         for (int e = 0; e < 4; ++e) { o1[e] = lat ? x1[e] * cs[e] - x2[e] * sn[e] : x1[e]; o2[e] = lat ? x2[e] * cs[e] + x1[e] * sn[e] : x2[e]; o1[e] *= sc; o2[e] *= sc; }
;                         u32x2v w1, w2; w1.x = pk2e(o1[0], o1[1]); w1.y = pk2e(o1[2], o1[3]); w2.x = pk2e(o2[0], o2[1]); w2.y = pk2e(o2[2], o2[3]);
;                         *(u32x2v*)(rowp + bj * HALF) = w1; *(u32x2v*)(rowp + bj * HALF + 16) = w2;
	v_pk_mul_f32 v[128:129], v[128:129], v[124:125]
	s_nop 0
	v_sub_f32_e32 v123, v128, v129
	v_mov_b32_e32 v128, v104
	v_mov_b32_e32 v129, v108
	v_pk_mul_f32 v[124:125], v[128:129], v[124:125]
	v_cndmask_b32_e32 v123, v108, v123, vcc
	v_add_f32_e32 v108, v125, v124
	v_cndmask_b32_e32 v104, v104, v108, vcc
	v_mul_f32_e32 v128, v150, v104
	v_mov_b32_e32 v104, v109
	v_pk_mul_f32 v[124:125], v[104:105], v[126:127]
	v_mov_b32_e32 v108, v105
	v_sub_f32_e32 v104, v124, v125
	v_cndmask_b32_e32 v104, v109, v104, vcc
	v_pk_mul_f32 v[108:109], v[108:109], v[126:127]
	v_mul_f32_e32 v123, v150, v123
	v_add_f32_e32 v108, v109, v108
	v_cndmask_b32_e32 v105, v105, v108, vcc
	v_mul_f32_e32 v108, v150, v104
	v_mul_f32_e32 v109, v150, v105
	v_mov_b32_e32 v104, v110
	v_mov_b32_e32 v105, v106
	v_pk_mul_f32 v[104:105], v[104:105], v[114:115]
	s_nop 0
	v_sub_f32_e32 v104, v104, v105
	v_cndmask_b32_e32 v124, v110, v104, vcc
	v_mov_b32_e32 v104, v106
	v_mov_b32_e32 v105, v110
	v_pk_mul_f32 v[104:105], v[104:105], v[114:115]
	v_mov_b32_e32 v110, v107
	v_add_f32_e32 v104, v105, v104
	v_cndmask_b32_e32 v104, v106, v104, vcc
	v_mov_b32_e32 v106, v111
	v_mul_f32_e32 v115, v150, v104
	v_pk_mul_f32 v[104:105], v[106:107], v[116:117]
	v_mul_f32_e32 v114, v150, v124
	v_sub_f32_e32 v104, v104, v105
	v_cndmask_b32_e32 v106, v111, v104, vcc
	v_pk_mul_f32 v[104:105], v[110:111], v[116:117]
	s_nop 0
	v_add_f32_e32 v104, v105, v104
	v_cndmask_b32_e32 v104, v107, v104, vcc
	v_mul_f32_e32 v105, v150, v106
	v_mul_f32_e32 v107, v150, v104
	v_cvt_pk_bf16_f32 v104, v123, v108
	v_cvt_pk_bf16_f32 v105, v114, v105
	v_cvt_pk_bf16_f32 v106, v128, v109
	v_cvt_pk_bf16_f32 v107, v115, v107
	global_store_dwordx2 v[118:119], v[104:105], off
	global_store_dwordx2 v[118:119], v[106:107], off offset:32
	v_mov_b32_e32 v104, v164
	v_mov_b32_e32 v105, v165
	v_mov_b32_e32 v106, v166
	v_mov_b32_e32 v107, v167
	v_mov_b32_e32 v108, v168
	v_mov_b32_e32 v109, v169
	v_mov_b32_e32 v110, v170
	v_mov_b32_e32 v111, v171
	v_mov_b32_e32 v114, v100
	v_mov_b32_e32 v115, v96
	v_pk_mul_f32 v[114:115], v[114:115], v[108:109]
	s_nop 0
	v_sub_f32_e32 v114, v114, v115
	v_cndmask_b32_e32 v116, v100, v114, vcc
	v_mov_b32_e32 v114, v96
	v_mov_b32_e32 v115, v100
	v_pk_mul_f32 v[108:109], v[114:115], v[108:109]
	v_mul_f32_e32 v114, v150, v116
	v_add_f32_e32 v100, v109, v108
	v_cndmask_b32_e32 v96, v96, v100, vcc
	v_mul_f32_e32 v115, v150, v96
	v_mov_b32_e32 v96, v101
	v_pk_mul_f32 v[108:109], v[96:97], v[110:111]
	v_mov_b32_e32 v100, v97
	v_sub_f32_e32 v96, v108, v109
	v_cndmask_b32_e32 v96, v101, v96, vcc
	v_pk_mul_f32 v[100:101], v[100:101], v[110:111]
	v_mov_b32_e32 v110, v92
	v_add_f32_e32 v100, v101, v100
	v_cndmask_b32_e32 v97, v97, v100, vcc
	v_mul_f32_e32 v100, v150, v96
	v_mul_f32_e32 v101, v150, v97
	v_mov_b32_e32 v96, v102
	v_mov_b32_e32 v97, v98
	v_pk_mul_f32 v[96:97], v[96:97], v[104:105]
	v_mov_b32_e32 v111, v88
	v_sub_f32_e32 v96, v96, v97
	v_cndmask_b32_e32 v108, v102, v96, vcc
	v_mov_b32_e32 v96, v98
	v_mov_b32_e32 v97, v102
	v_pk_mul_f32 v[96:97], v[96:97], v[104:105]
	v_mov_b32_e32 v102, v99
	v_add_f32_e32 v96, v97, v96
	v_cndmask_b32_e32 v96, v98, v96, vcc
	v_mov_b32_e32 v98, v103
	v_mul_f32_e32 v105, v150, v96
	v_pk_mul_f32 v[96:97], v[98:99], v[106:107]
	v_mul_f32_e32 v104, v150, v108
	v_sub_f32_e32 v96, v96, v97
	v_cndmask_b32_e32 v98, v103, v96, vcc
	v_pk_mul_f32 v[96:97], v[102:103], v[106:107]
	s_nop 0
	v_add_f32_e32 v96, v97, v96
	v_cndmask_b32_e32 v96, v99, v96, vcc
	v_mul_f32_e32 v97, v150, v98
	v_mul_f32_e32 v99, v150, v96
	v_cvt_pk_bf16_f32 v96, v114, v100
	v_cvt_pk_bf16_f32 v97, v104, v97
	v_or_b32_e32 v104, 32, v151
	v_cvt_pk_bf16_f32 v98, v115, v101
	v_cvt_pk_bf16_f32 v99, v105, v99
	global_store_dwordx2 v[118:119], v[96:97], off offset:256
	global_store_dwordx2 v[118:119], v[98:99], off offset:288
	v_or_b32_e32 v96, s0, v104
	v_ashrrev_i32_e32 v97, 31, v96
	v_cmp_gt_i32_e32 vcc, s80, v96
	v_lshlrev_b64 v[96:97], 11, v[96:97]
	v_lshl_add_u64 v[100:101], v[142:143], 0, v[96:97]
	v_cndmask_b32_e64 v96, v104, v141, s[4:5]
	v_lshl_add_u32 v96, v96, 4, v140
	v_ashrrev_i32_e32 v97, 31, v96
	v_lshl_add_u64 v[102:103], v[96:97], 3, s[6:7]
	global_load_dwordx4 v[96:99], v[102:103], off offset:16
	global_load_dwordx4 v[106:109], v[102:103], off
	global_load_dwordx4 v[164:167], v[102:103], off offset:16
	global_load_dwordx4 v[168:171], v[102:103], off
	s_waitcnt vmcnt(0)
; __device__ __forceinline__ unsigned pk2e(float lo, float hi) { typedef float v2f __attribute__((ext_vector_type(2))); typedef __bf16 v2b __attribute__((ext_vector_type(2))); v2f v = {lo, hi}; v2b b = __builtin_convertvector(v, v2b); return __builtin_bit_cast(unsigned, b); }
;     __device__ __forceinline__ void operator()(const f32x4 (&acc)[2][2][4][2], const Unit& u, int wr, int wc, int fr_, int fq_) const {
;     ...
; #pragma unroll
;         for (int ai = 0; ai < 2; ++ai)
; #pragma unroll
;             for (int m = 0; m < 4; ++m) {
;                 const int row = u.pm * BM + ai * HALF + wr * 64 + m * 16 + fr;
;                 const bool lat = row < tlat; const int s = row & 4095, prow = s >> 6, pcol = s & 63;
;                 bf16_t* rowp = base + (size_t)row * ld + colt + wc * 32 + 4 * fq;
; #pragma unroll
;                 for (int bj = 0; bj < 2; ++bj) {
;                     if (MODE == 0) {
;                         const int pos = (wc & 1) ? pcol : prow;
;                         const f32x4* tp = (const f32x4*)(tab + (size_t)(pos * 16 + 4 * fq) * 2);
;                         const f32x4 t0 = tp[0], t1 = tp[1];
;                         const f32x4 x1 = acc[ai][bj][m][0], x2 = acc[ai][bj][m][1];
;                         const float cs[4] = {t0[0], t0[2], t1[0], t1[2]}, sn[4] = {t0[1], t0[3], t1[1], t1[3]};
;                         float o1[4], o2[4];
; #pragma unroll
;                         for (int e = 0; e < 4; ++e) { o1[e] = lat ? x1[e] * cs[e] - x2[e] * sn[e] : x1[e]; o2[e] = lat ? x2[e] * cs[e] + x1[e] * sn[e] : x2[e]; o1[e] *= sc; o2[e] *= sc; }
;                         u32x2v w1, w2; w1.x = pk2e(o1[0], o1[1]); w1.y = pk2e(o1[2], o1[3]); w2.x = pk2e(o2[0], o2[1]); w2.y = pk2e(o2[2], o2[3]);
;                         *(u32x2v*)(rowp + bj * HALF) = w1; *(u32x2v*)(rowp + bj * HALF + 16) = w2;
	v_pk_mul_f32 v[110:111], v[110:111], v[106:107]
	s_nop 0
	v_sub_f32_e32 v105, v110, v111
	v_mov_b32_e32 v110, v88
	v_mov_b32_e32 v111, v92
	v_pk_mul_f32 v[106:107], v[110:111], v[106:107]
	v_cndmask_b32_e32 v105, v92, v105, vcc
	v_add_f32_e32 v92, v107, v106
	v_cndmask_b32_e32 v88, v88, v92, vcc
	v_mul_f32_e32 v110, v150, v88
	v_mov_b32_e32 v88, v93
	v_pk_mul_f32 v[106:107], v[88:89], v[108:109]
	v_mov_b32_e32 v92, v89
	v_sub_f32_e32 v88, v106, v107
	v_cndmask_b32_e32 v88, v93, v88, vcc
	v_pk_mul_f32 v[92:93], v[92:93], v[108:109]
	v_mul_f32_e32 v105, v150, v105
	v_add_f32_e32 v92, v93, v92
	v_cndmask_b32_e32 v89, v89, v92, vcc
	v_mul_f32_e32 v92, v150, v88
	v_mul_f32_e32 v93, v150, v89
	v_mov_b32_e32 v88, v94
	v_mov_b32_e32 v89, v90
	v_pk_mul_f32 v[88:89], v[88:89], v[96:97]
	s_nop 0
	v_sub_f32_e32 v88, v88, v89
	v_cndmask_b32_e32 v106, v94, v88, vcc
	v_mov_b32_e32 v88, v90
	v_mov_b32_e32 v89, v94
	v_pk_mul_f32 v[88:89], v[88:89], v[96:97]
	v_mov_b32_e32 v94, v91
	v_add_f32_e32 v88, v89, v88
	v_cndmask_b32_e32 v88, v90, v88, vcc
	v_mov_b32_e32 v90, v95
	v_mul_f32_e32 v97, v150, v88
	v_pk_mul_f32 v[88:89], v[90:91], v[98:99]
	v_mul_f32_e32 v96, v150, v106
	v_sub_f32_e32 v88, v88, v89
	v_cndmask_b32_e32 v90, v95, v88, vcc
	v_pk_mul_f32 v[88:89], v[94:95], v[98:99]
	s_nop 0
	v_add_f32_e32 v88, v89, v88
	v_cndmask_b32_e32 v88, v91, v88, vcc
	v_mul_f32_e32 v89, v150, v90
	v_mul_f32_e32 v91, v150, v88
	v_cvt_pk_bf16_f32 v88, v105, v92
	v_cvt_pk_bf16_f32 v89, v96, v89
	v_cvt_pk_bf16_f32 v90, v110, v93
	v_cvt_pk_bf16_f32 v91, v97, v91
	global_store_dwordx2 v[100:101], v[88:89], off
	global_store_dwordx2 v[100:101], v[90:91], off offset:32
	v_mov_b32_e32 v88, v164
	v_mov_b32_e32 v89, v165
	v_mov_b32_e32 v90, v166
	v_mov_b32_e32 v91, v167
	v_mov_b32_e32 v92, v168
	v_mov_b32_e32 v93, v169
	v_mov_b32_e32 v94, v170
	v_mov_b32_e32 v95, v171
	v_mov_b32_e32 v96, v84
	v_mov_b32_e32 v97, v80
	v_pk_mul_f32 v[96:97], v[96:97], v[92:93]
	s_nop 0
	v_sub_f32_e32 v96, v96, v97
	v_cndmask_b32_e32 v98, v84, v96, vcc
	v_mov_b32_e32 v96, v80
	v_mov_b32_e32 v97, v84
	v_pk_mul_f32 v[92:93], v[96:97], v[92:93]
	v_mul_f32_e32 v96, v150, v98
	v_add_f32_e32 v84, v93, v92
	v_cndmask_b32_e32 v80, v80, v84, vcc
	v_mul_f32_e32 v97, v150, v80
	v_mov_b32_e32 v80, v85
	v_pk_mul_f32 v[92:93], v[80:81], v[94:95]
	v_mov_b32_e32 v84, v81
	v_sub_f32_e32 v80, v92, v93
	v_cndmask_b32_e32 v80, v85, v80, vcc
	v_pk_mul_f32 v[84:85], v[84:85], v[94:95]
	v_mov_b32_e32 v94, v76
	v_add_f32_e32 v84, v85, v84
	v_cndmask_b32_e32 v81, v81, v84, vcc
	v_mul_f32_e32 v84, v150, v80
	v_mul_f32_e32 v85, v150, v81
	v_mov_b32_e32 v80, v86
	v_mov_b32_e32 v81, v82
	v_pk_mul_f32 v[80:81], v[80:81], v[88:89]
	v_mov_b32_e32 v95, v72
	v_sub_f32_e32 v80, v80, v81
	v_cndmask_b32_e32 v92, v86, v80, vcc
	v_mov_b32_e32 v80, v82
	v_mov_b32_e32 v81, v86
	v_pk_mul_f32 v[80:81], v[80:81], v[88:89]
	v_mov_b32_e32 v86, v83
	v_add_f32_e32 v80, v81, v80
	v_cndmask_b32_e32 v80, v82, v80, vcc
	v_mov_b32_e32 v82, v87
	v_mul_f32_e32 v89, v150, v80
	v_pk_mul_f32 v[80:81], v[82:83], v[90:91]
	v_mul_f32_e32 v88, v150, v92
	v_sub_f32_e32 v80, v80, v81
	v_cndmask_b32_e32 v82, v87, v80, vcc
	v_pk_mul_f32 v[80:81], v[86:87], v[90:91]
	s_nop 0
	v_add_f32_e32 v80, v81, v80
	v_cndmask_b32_e32 v80, v83, v80, vcc
	v_mul_f32_e32 v81, v150, v82
	v_mul_f32_e32 v83, v150, v80
	v_cvt_pk_bf16_f32 v80, v96, v84
	v_cvt_pk_bf16_f32 v81, v88, v81
	v_or_b32_e32 v88, 48, v151
	v_cvt_pk_bf16_f32 v82, v97, v85
	v_cvt_pk_bf16_f32 v83, v89, v83
	global_store_dwordx2 v[100:101], v[80:81], off offset:256
	global_store_dwordx2 v[100:101], v[82:83], off offset:288
	v_or_b32_e32 v80, s0, v88
	v_ashrrev_i32_e32 v81, 31, v80
	v_cmp_gt_i32_e32 vcc, s80, v80
	v_lshlrev_b64 v[80:81], 11, v[80:81]
	v_lshl_add_u64 v[84:85], v[142:143], 0, v[80:81]
	v_cndmask_b32_e64 v80, v88, v141, s[4:5]
	v_lshl_add_u32 v80, v80, 4, v140
	v_ashrrev_i32_e32 v81, 31, v80
	v_lshl_add_u64 v[86:87], v[80:81], 3, s[6:7]
	global_load_dwordx4 v[80:83], v[86:87], off offset:16
	global_load_dwordx4 v[90:93], v[86:87], off
	global_load_dwordx4 v[164:167], v[86:87], off offset:16
	global_load_dwordx4 v[168:171], v[86:87], off
	s_addk_i32 s0, 0x80
	s_bfe_u32 s1, s0, 0x60006
	s_waitcnt vmcnt(0)
	v_pk_mul_f32 v[94:95], v[94:95], v[90:91]
	s_nop 0
	v_sub_f32_e32 v89, v94, v95
	v_mov_b32_e32 v94, v72
	v_mov_b32_e32 v95, v76
	v_pk_mul_f32 v[90:91], v[94:95], v[90:91]
	v_cndmask_b32_e32 v89, v76, v89, vcc
	v_add_f32_e32 v76, v91, v90
	v_cndmask_b32_e32 v72, v72, v76, vcc
	v_mul_f32_e32 v94, v150, v72
	v_mov_b32_e32 v72, v77
	v_pk_mul_f32 v[90:91], v[72:73], v[92:93]
	v_mov_b32_e32 v76, v73
	v_sub_f32_e32 v72, v90, v91
	v_cndmask_b32_e32 v72, v77, v72, vcc
	v_pk_mul_f32 v[76:77], v[76:77], v[92:93]
	v_mul_f32_e32 v89, v150, v89
	v_add_f32_e32 v76, v77, v76
	v_cndmask_b32_e32 v73, v73, v76, vcc
	v_mul_f32_e32 v76, v150, v72
	v_mul_f32_e32 v77, v150, v73
	v_mov_b32_e32 v72, v78
	v_mov_b32_e32 v73, v74
	v_pk_mul_f32 v[72:73], v[72:73], v[80:81]
	s_nop 0
	v_sub_f32_e32 v72, v72, v73
	v_cndmask_b32_e32 v90, v78, v72, vcc
	v_mov_b32_e32 v72, v74
	v_mov_b32_e32 v73, v78
	v_pk_mul_f32 v[72:73], v[72:73], v[80:81]
	v_mov_b32_e32 v78, v75
	v_add_f32_e32 v72, v73, v72
	v_cndmask_b32_e32 v72, v74, v72, vcc
	v_mov_b32_e32 v74, v79
	v_mul_f32_e32 v81, v150, v72
	v_pk_mul_f32 v[72:73], v[74:75], v[82:83]
	v_mul_f32_e32 v80, v150, v90
	v_sub_f32_e32 v72, v72, v73
	v_cndmask_b32_e32 v74, v79, v72, vcc
	v_pk_mul_f32 v[72:73], v[78:79], v[82:83]
	s_nop 0
	v_add_f32_e32 v72, v73, v72
	v_cndmask_b32_e32 v72, v75, v72, vcc
	v_mul_f32_e32 v73, v150, v74
	v_mul_f32_e32 v75, v150, v72
	v_cvt_pk_bf16_f32 v72, v89, v76
; __device__ __forceinline__ unsigned pk2e(float lo, float hi) { typedef float v2f __attribute__((ext_vector_type(2))); typedef __bf16 v2b __attribute__((ext_vector_type(2))); v2f v = {lo, hi}; v2b b = __builtin_convertvector(v, v2b); return __builtin_bit_cast(unsigned, b); }
;     __device__ __forceinline__ void operator()(const f32x4 (&acc)[2][2][4][2], const Unit& u, int wr, int wc, int fr_, int fq_) const {
;     ...
; #pragma unroll
;         for (int ai = 0; ai < 2; ++ai)
; #pragma unroll
;             for (int m = 0; m < 4; ++m) {
;                 const int row = u.pm * BM + ai * HALF + wr * 64 + m * 16 + fr;
;                 const bool lat = row < tlat; const int s = row & 4095, prow = s >> 6, pcol = s & 63;
;                 bf16_t* rowp = base + (size_t)row * ld + colt + wc * 32 + 4 * fq;
; #pragma unroll
;                 for (int bj = 0; bj < 2; ++bj) {
;                     if (MODE == 0) {
;                         const int pos = (wc & 1) ? pcol : prow;
;                         const f32x4* tp = (const f32x4*)(tab + (size_t)(pos * 16 + 4 * fq) * 2);
;                         const f32x4 t0 = tp[0], t1 = tp[1];
;                         const f32x4 x1 = acc[ai][bj][m][0], x2 = acc[ai][bj][m][1];
;                         const float cs[4] = {t0[0], t0[2], t1[0], t1[2]}, sn[4] = {t0[1], t0[3], t1[1], t1[3]};
;                         float o1[4], o2[4];
; #pragma unroll
;                         for (int e = 0; e < 4; ++e) { o1[e] = lat ? x1[e] * cs[e] - x2[e] * sn[e] : x1[e]; o2[e] = lat ? x2[e] * cs[e] + x1[e] * sn[e] : x2[e]; o1[e] *= sc; o2[e] *= sc; }
;                         u32x2v w1, w2; w1.x = pk2e(o1[0], o1[1]); w1.y = pk2e(o1[2], o1[3]); w2.x = pk2e(o2[0], o2[1]); w2.y = pk2e(o2[2], o2[3]);
;                         *(u32x2v*)(rowp + bj * HALF) = w1; *(u32x2v*)(rowp + bj * HALF + 16) = w2;
	v_cvt_pk_bf16_f32 v73, v80, v73
	v_cvt_pk_bf16_f32 v74, v94, v77
	v_cvt_pk_bf16_f32 v75, v81, v75
	global_store_dwordx2 v[84:85], v[72:73], off
	global_store_dwordx2 v[84:85], v[74:75], off offset:32
	v_mov_b32_e32 v72, v164
	v_mov_b32_e32 v73, v165
	v_mov_b32_e32 v74, v166
	v_mov_b32_e32 v75, v167
	v_mov_b32_e32 v76, v168
	v_mov_b32_e32 v77, v169
	v_mov_b32_e32 v78, v170
	v_mov_b32_e32 v79, v171
	v_mov_b32_e32 v80, v68
	v_mov_b32_e32 v81, v64
	v_pk_mul_f32 v[80:81], v[80:81], v[76:77]
	s_nop 0
	v_sub_f32_e32 v80, v80, v81
	v_cndmask_b32_e32 v82, v68, v80, vcc
	v_mov_b32_e32 v80, v64
	v_mov_b32_e32 v81, v68
	v_pk_mul_f32 v[76:77], v[80:81], v[76:77]
	v_mul_f32_e32 v80, v150, v82
	v_add_f32_e32 v68, v77, v76
	v_cndmask_b32_e32 v64, v64, v68, vcc
	v_mul_f32_e32 v81, v150, v64
	v_mov_b32_e32 v64, v69
	v_pk_mul_f32 v[76:77], v[64:65], v[78:79]
	v_mov_b32_e32 v68, v65
	v_sub_f32_e32 v64, v76, v77
	v_cndmask_b32_e32 v64, v69, v64, vcc
	v_pk_mul_f32 v[68:69], v[68:69], v[78:79]
	v_mov_b32_e32 v78, v60
	v_add_f32_e32 v68, v69, v68
	v_cndmask_b32_e32 v65, v65, v68, vcc
	v_mul_f32_e32 v68, v150, v64
	v_mul_f32_e32 v69, v150, v65
	v_mov_b32_e32 v64, v70
	v_mov_b32_e32 v65, v66
	v_pk_mul_f32 v[64:65], v[64:65], v[72:73]
	v_mov_b32_e32 v79, v56
	v_sub_f32_e32 v64, v64, v65
	v_cndmask_b32_e32 v76, v70, v64, vcc
	v_mov_b32_e32 v64, v66
	v_mov_b32_e32 v65, v70
	v_pk_mul_f32 v[64:65], v[64:65], v[72:73]
	v_mov_b32_e32 v70, v67
	v_add_f32_e32 v64, v65, v64
	v_cndmask_b32_e32 v64, v66, v64, vcc
	v_mov_b32_e32 v66, v71
	v_mul_f32_e32 v73, v150, v64
	v_pk_mul_f32 v[64:65], v[66:67], v[74:75]
	v_mul_f32_e32 v72, v150, v76
	v_sub_f32_e32 v64, v64, v65
	v_cndmask_b32_e32 v66, v71, v64, vcc
	v_pk_mul_f32 v[64:65], v[70:71], v[74:75]
	s_nop 0
	v_add_f32_e32 v64, v65, v64
	v_cndmask_b32_e32 v64, v67, v64, vcc
	v_mul_f32_e32 v65, v150, v66
	v_mul_f32_e32 v67, v150, v64
	v_cvt_pk_bf16_f32 v64, v80, v68
	v_cvt_pk_bf16_f32 v65, v72, v65
	v_cvt_pk_bf16_f32 v66, v81, v69
	v_cvt_pk_bf16_f32 v67, v73, v67
	global_store_dwordx2 v[84:85], v[64:65], off offset:256
	global_store_dwordx2 v[84:85], v[66:67], off offset:288
	v_or_b32_e32 v64, s0, v151
	v_ashrrev_i32_e32 v65, 31, v64
	v_cmp_gt_i32_e32 vcc, s80, v64
	v_lshlrev_b64 v[64:65], 11, v[64:65]
	v_mov_b32_e32 v72, s1
	v_lshl_add_u64 v[68:69], v[142:143], 0, v[64:65]
	v_cndmask_b32_e64 v64, v151, v72, s[4:5]
	v_lshl_add_u32 v64, v64, 4, v140
	v_ashrrev_i32_e32 v65, 31, v64
	v_lshl_add_u64 v[70:71], v[64:65], 3, s[6:7]
	global_load_dwordx4 v[64:67], v[70:71], off offset:16
	global_load_dwordx4 v[74:77], v[70:71], off
	global_load_dwordx4 v[164:167], v[70:71], off offset:16
	global_load_dwordx4 v[168:171], v[70:71], off
	s_waitcnt vmcnt(0)
	v_pk_mul_f32 v[78:79], v[78:79], v[74:75]
	s_nop 0
	v_sub_f32_e32 v73, v78, v79
	v_mov_b32_e32 v78, v56
	v_mov_b32_e32 v79, v60
	v_pk_mul_f32 v[74:75], v[78:79], v[74:75]
	v_cndmask_b32_e32 v73, v60, v73, vcc
	v_add_f32_e32 v60, v75, v74
	v_cndmask_b32_e32 v56, v56, v60, vcc
	v_mul_f32_e32 v78, v150, v56
	v_mov_b32_e32 v56, v61
	v_pk_mul_f32 v[74:75], v[56:57], v[76:77]
	v_mov_b32_e32 v60, v57
	v_sub_f32_e32 v56, v74, v75
	v_cndmask_b32_e32 v56, v61, v56, vcc
	v_pk_mul_f32 v[60:61], v[60:61], v[76:77]
	v_mul_f32_e32 v73, v150, v73
	v_add_f32_e32 v60, v61, v60
	v_cndmask_b32_e32 v57, v57, v60, vcc
	v_mul_f32_e32 v60, v150, v56
	v_mul_f32_e32 v61, v150, v57
	v_mov_b32_e32 v56, v62
	v_mov_b32_e32 v57, v58
	v_pk_mul_f32 v[56:57], v[56:57], v[64:65]
	s_nop 0
	v_sub_f32_e32 v56, v56, v57
	v_cndmask_b32_e32 v74, v62, v56, vcc
	v_mov_b32_e32 v56, v58
	v_mov_b32_e32 v57, v62
	v_pk_mul_f32 v[56:57], v[56:57], v[64:65]
	v_mov_b32_e32 v62, v59
	v_add_f32_e32 v56, v57, v56
	v_cndmask_b32_e32 v56, v58, v56, vcc
	v_mov_b32_e32 v58, v63
	v_mul_f32_e32 v65, v150, v56
	v_pk_mul_f32 v[56:57], v[58:59], v[66:67]
	v_mul_f32_e32 v64, v150, v74
	v_sub_f32_e32 v56, v56, v57
	v_cndmask_b32_e32 v58, v63, v56, vcc
	v_pk_mul_f32 v[56:57], v[62:63], v[66:67]
	s_nop 0
	v_add_f32_e32 v56, v57, v56
	v_cndmask_b32_e32 v56, v59, v56, vcc
	v_mul_f32_e32 v57, v150, v58
	v_mul_f32_e32 v59, v150, v56
	v_cvt_pk_bf16_f32 v56, v73, v60
	v_cvt_pk_bf16_f32 v57, v64, v57
	v_cvt_pk_bf16_f32 v58, v78, v61
	v_cvt_pk_bf16_f32 v59, v65, v59
	global_store_dwordx2 v[68:69], v[56:57], off
	global_store_dwordx2 v[68:69], v[58:59], off offset:32
	v_mov_b32_e32 v56, v164
	v_mov_b32_e32 v57, v165
	v_mov_b32_e32 v58, v166
	v_mov_b32_e32 v59, v167
	v_mov_b32_e32 v60, v168
	v_mov_b32_e32 v61, v169
	v_mov_b32_e32 v62, v170
	v_mov_b32_e32 v63, v171
	v_mov_b32_e32 v64, v52
	v_mov_b32_e32 v65, v48
	v_pk_mul_f32 v[64:65], v[64:65], v[60:61]
	s_nop 0
	v_sub_f32_e32 v64, v64, v65
	v_cndmask_b32_e32 v66, v52, v64, vcc
	v_mov_b32_e32 v64, v48
	v_mov_b32_e32 v65, v52
	v_pk_mul_f32 v[60:61], v[64:65], v[60:61]
	v_mul_f32_e32 v64, v150, v66
	v_add_f32_e32 v52, v61, v60
	v_cndmask_b32_e32 v48, v48, v52, vcc
	v_mul_f32_e32 v65, v150, v48
	v_mov_b32_e32 v48, v53
	v_pk_mul_f32 v[60:61], v[48:49], v[62:63]
	v_mov_b32_e32 v52, v49
	v_sub_f32_e32 v48, v60, v61
	v_cndmask_b32_e32 v48, v53, v48, vcc
	v_pk_mul_f32 v[52:53], v[52:53], v[62:63]
	v_mov_b32_e32 v61, v40
	v_add_f32_e32 v52, v53, v52
	v_cndmask_b32_e32 v49, v49, v52, vcc
	v_mul_f32_e32 v52, v150, v48
	v_mul_f32_e32 v53, v150, v49
	v_mov_b32_e32 v48, v54
	v_mov_b32_e32 v49, v50
	v_pk_mul_f32 v[48:49], v[48:49], v[56:57]
	s_nop 0
	v_sub_f32_e32 v48, v48, v49
	v_cndmask_b32_e32 v60, v54, v48, vcc
	v_mov_b32_e32 v48, v50
	v_mov_b32_e32 v49, v54
	v_pk_mul_f32 v[48:49], v[48:49], v[56:57]
	v_mov_b32_e32 v54, v51
	v_add_f32_e32 v48, v49, v48
	v_cndmask_b32_e32 v48, v50, v48, vcc
	v_mov_b32_e32 v50, v55
	v_mul_f32_e32 v57, v150, v48
	v_pk_mul_f32 v[48:49], v[50:51], v[58:59]
	v_mul_f32_e32 v56, v150, v60
	v_sub_f32_e32 v48, v48, v49
	v_cndmask_b32_e32 v50, v55, v48, vcc
	v_pk_mul_f32 v[48:49], v[54:55], v[58:59]
	v_mov_b32_e32 v60, v44
	v_add_f32_e32 v48, v49, v48
	v_cndmask_b32_e32 v48, v51, v48, vcc
	v_mul_f32_e32 v49, v150, v50
	v_mul_f32_e32 v51, v150, v48
	v_cvt_pk_bf16_f32 v48, v64, v52
	v_cvt_pk_bf16_f32 v49, v56, v49
	v_cvt_pk_bf16_f32 v50, v65, v53
	v_cvt_pk_bf16_f32 v51, v57, v51
	global_store_dwordx2 v[68:69], v[48:49], off offset:256
	global_store_dwordx2 v[68:69], v[50:51], off offset:288
	v_or_b32_e32 v48, s0, v122
	v_ashrrev_i32_e32 v49, 31, v48
	v_cmp_gt_i32_e32 vcc, s80, v48
	v_lshlrev_b64 v[48:49], 11, v[48:49]
	v_lshl_add_u64 v[52:53], v[142:143], 0, v[48:49]
	v_cndmask_b32_e64 v48, v122, v72, s[4:5]
	v_lshl_add_u32 v48, v48, 4, v140
	v_ashrrev_i32_e32 v49, 31, v48
	v_lshl_add_u64 v[54:55], v[48:49], 3, s[6:7]
	global_load_dwordx4 v[48:51], v[54:55], off offset:16
	global_load_dwordx4 v[56:59], v[54:55], off
	global_load_dwordx4 v[164:167], v[54:55], off offset:16
	global_load_dwordx4 v[168:171], v[54:55], off
	s_waitcnt vmcnt(0)
; __device__ __forceinline__ unsigned pk2e(float lo, float hi) { typedef float v2f __attribute__((ext_vector_type(2))); typedef __bf16 v2b __attribute__((ext_vector_type(2))); v2f v = {lo, hi}; v2b b = __builtin_convertvector(v, v2b); return __builtin_bit_cast(unsigned, b); }
;     __device__ __forceinline__ void operator()(const f32x4 (&acc)[2][2][4][2], const Unit& u, int wr, int wc, int fr_, int fq_) const {
;     ...
; #pragma unroll
;         for (int ai = 0; ai < 2; ++ai)
; #pragma unroll
;             for (int m = 0; m < 4; ++m) {
;                 const int row = u.pm * BM + ai * HALF + wr * 64 + m * 16 + fr;
;                 const bool lat = row < tlat; const int s = row & 4095, prow = s >> 6, pcol = s & 63;
;                 bf16_t* rowp = base + (size_t)row * ld + colt + wc * 32 + 4 * fq;
; #pragma unroll
;                 for (int bj = 0; bj < 2; ++bj) {
;                     if (MODE == 0) {
;                         const int pos = (wc & 1) ? pcol : prow;
;                         const f32x4* tp = (const f32x4*)(tab + (size_t)(pos * 16 + 4 * fq) * 2);
;                         const f32x4 t0 = tp[0], t1 = tp[1];
;                         const f32x4 x1 = acc[ai][bj][m][0], x2 = acc[ai][bj][m][1];
;                         const float cs[4] = {t0[0], t0[2], t1[0], t1[2]}, sn[4] = {t0[1], t0[3], t1[1], t1[3]};
;                         float o1[4], o2[4];
; #pragma unroll
;                         for (int e = 0; e < 4; ++e) { o1[e] = lat ? x1[e] * cs[e] - x2[e] * sn[e] : x1[e]; o2[e] = lat ? x2[e] * cs[e] + x1[e] * sn[e] : x2[e]; o1[e] *= sc; o2[e] *= sc; }
;                         u32x2v w1, w2; w1.x = pk2e(o1[0], o1[1]); w1.y = pk2e(o1[2], o1[3]); w2.x = pk2e(o2[0], o2[1]); w2.y = pk2e(o2[2], o2[3]);
;                         *(u32x2v*)(rowp + bj * HALF) = w1; *(u32x2v*)(rowp + bj * HALF + 16) = w2;
	v_pk_mul_f32 v[60:61], v[60:61], v[56:57]
	s_nop 0
	v_sub_f32_e32 v60, v60, v61
	v_cndmask_b32_e32 v62, v44, v60, vcc
	v_mov_b32_e32 v60, v40
	v_mov_b32_e32 v61, v44
	v_pk_mul_f32 v[56:57], v[60:61], v[56:57]
	v_mul_f32_e32 v60, v150, v62
	v_add_f32_e32 v44, v57, v56
	v_cndmask_b32_e32 v40, v40, v44, vcc
	v_mul_f32_e32 v61, v150, v40
	v_mov_b32_e32 v40, v45
	v_pk_mul_f32 v[56:57], v[40:41], v[58:59]
	v_mov_b32_e32 v44, v41
	v_sub_f32_e32 v40, v56, v57
	v_cndmask_b32_e32 v40, v45, v40, vcc
	v_pk_mul_f32 v[44:45], v[44:45], v[58:59]
	s_nop 0
	v_add_f32_e32 v44, v45, v44
	v_cndmask_b32_e32 v41, v41, v44, vcc
	v_mul_f32_e32 v44, v150, v40
	v_mul_f32_e32 v45, v150, v41
	v_mov_b32_e32 v40, v46
	v_mov_b32_e32 v41, v42
	v_pk_mul_f32 v[40:41], v[40:41], v[48:49]
	s_nop 0
	v_sub_f32_e32 v40, v40, v41
	v_cndmask_b32_e32 v56, v46, v40, vcc
	v_mov_b32_e32 v40, v42
	v_mov_b32_e32 v41, v46
	v_pk_mul_f32 v[40:41], v[40:41], v[48:49]
	v_mov_b32_e32 v46, v43
	v_add_f32_e32 v40, v41, v40
	v_cndmask_b32_e32 v40, v42, v40, vcc
	v_mov_b32_e32 v42, v47
	v_mul_f32_e32 v49, v150, v40
	v_pk_mul_f32 v[40:41], v[42:43], v[50:51]
	v_mul_f32_e32 v48, v150, v56
	v_sub_f32_e32 v40, v40, v41
	v_cndmask_b32_e32 v42, v47, v40, vcc
	v_pk_mul_f32 v[40:41], v[46:47], v[50:51]
	s_nop 0
	v_add_f32_e32 v40, v41, v40
	v_cndmask_b32_e32 v40, v43, v40, vcc
	v_mul_f32_e32 v41, v150, v42
	v_mul_f32_e32 v43, v150, v40
	v_cvt_pk_bf16_f32 v40, v60, v44
	v_cvt_pk_bf16_f32 v41, v48, v41
	v_cvt_pk_bf16_f32 v42, v61, v45
	v_cvt_pk_bf16_f32 v43, v49, v43
	global_store_dwordx2 v[52:53], v[40:41], off
	global_store_dwordx2 v[52:53], v[42:43], off offset:32
	v_mov_b32_e32 v40, v164
	v_mov_b32_e32 v41, v165
	v_mov_b32_e32 v42, v166
	v_mov_b32_e32 v43, v167
	v_mov_b32_e32 v44, v168
	v_mov_b32_e32 v45, v169
	v_mov_b32_e32 v46, v170
	v_mov_b32_e32 v47, v171
	v_mov_b32_e32 v48, v36
	v_mov_b32_e32 v49, v32
	v_pk_mul_f32 v[48:49], v[48:49], v[44:45]
	s_nop 0
	v_sub_f32_e32 v48, v48, v49
	v_cndmask_b32_e32 v50, v36, v48, vcc
	v_mov_b32_e32 v48, v32
	v_mov_b32_e32 v49, v36
	v_pk_mul_f32 v[44:45], v[48:49], v[44:45]
	v_mul_f32_e32 v48, v150, v50
	v_add_f32_e32 v36, v45, v44
	v_cndmask_b32_e32 v32, v32, v36, vcc
	v_mul_f32_e32 v49, v150, v32
	v_mov_b32_e32 v32, v37
	v_pk_mul_f32 v[44:45], v[32:33], v[46:47]
	v_mov_b32_e32 v36, v33
	v_sub_f32_e32 v32, v44, v45
	v_cndmask_b32_e32 v32, v37, v32, vcc
	v_pk_mul_f32 v[36:37], v[36:37], v[46:47]
	v_mov_b32_e32 v45, v24
	v_add_f32_e32 v36, v37, v36
	v_cndmask_b32_e32 v33, v33, v36, vcc
	v_mul_f32_e32 v36, v150, v32
	v_mul_f32_e32 v37, v150, v33
	v_mov_b32_e32 v32, v38
	v_mov_b32_e32 v33, v34
	v_pk_mul_f32 v[32:33], v[32:33], v[40:41]
	s_nop 0
	v_sub_f32_e32 v32, v32, v33
	v_cndmask_b32_e32 v44, v38, v32, vcc
	v_mov_b32_e32 v32, v34
	v_mov_b32_e32 v33, v38
	v_pk_mul_f32 v[32:33], v[32:33], v[40:41]
	v_mov_b32_e32 v38, v35
	v_add_f32_e32 v32, v33, v32
	v_cndmask_b32_e32 v32, v34, v32, vcc
	v_mov_b32_e32 v34, v39
	v_mul_f32_e32 v41, v150, v32
	v_pk_mul_f32 v[32:33], v[34:35], v[42:43]
	v_mul_f32_e32 v40, v150, v44
	v_sub_f32_e32 v32, v32, v33
	v_cndmask_b32_e32 v34, v39, v32, vcc
	v_pk_mul_f32 v[32:33], v[38:39], v[42:43]
	v_mov_b32_e32 v44, v28
	v_add_f32_e32 v32, v33, v32
	v_cndmask_b32_e32 v32, v35, v32, vcc
	v_mul_f32_e32 v33, v150, v34
	v_mul_f32_e32 v35, v150, v32
	v_cvt_pk_bf16_f32 v32, v48, v36
	v_cvt_pk_bf16_f32 v33, v40, v33
	v_cvt_pk_bf16_f32 v34, v49, v37
	v_cvt_pk_bf16_f32 v35, v41, v35
	global_store_dwordx2 v[52:53], v[32:33], off offset:256
	global_store_dwordx2 v[52:53], v[34:35], off offset:288
	v_or_b32_e32 v32, s0, v104
	v_ashrrev_i32_e32 v33, 31, v32
	v_cmp_gt_i32_e32 vcc, s80, v32
	v_lshlrev_b64 v[32:33], 11, v[32:33]
	v_lshl_add_u64 v[36:37], v[142:143], 0, v[32:33]
	v_cndmask_b32_e64 v32, v104, v72, s[4:5]
	v_lshl_add_u32 v32, v32, 4, v140
	v_ashrrev_i32_e32 v33, 31, v32
	v_lshl_add_u64 v[38:39], v[32:33], 3, s[6:7]
	global_load_dwordx4 v[32:35], v[38:39], off offset:16
	global_load_dwordx4 v[40:43], v[38:39], off
	global_load_dwordx4 v[164:167], v[38:39], off offset:16
	global_load_dwordx4 v[168:171], v[38:39], off
	s_waitcnt vmcnt(0)
	v_pk_mul_f32 v[44:45], v[44:45], v[40:41]
	s_nop 0
	v_sub_f32_e32 v44, v44, v45
	v_cndmask_b32_e32 v46, v28, v44, vcc
	v_mov_b32_e32 v44, v24
	v_mov_b32_e32 v45, v28
	v_pk_mul_f32 v[40:41], v[44:45], v[40:41]
	v_mul_f32_e32 v44, v150, v46
	v_add_f32_e32 v28, v41, v40
	v_cndmask_b32_e32 v24, v24, v28, vcc
	v_mul_f32_e32 v45, v150, v24
	v_mov_b32_e32 v24, v29
	v_pk_mul_f32 v[40:41], v[24:25], v[42:43]
	v_mov_b32_e32 v28, v25
	v_sub_f32_e32 v24, v40, v41
	v_cndmask_b32_e32 v24, v29, v24, vcc
	v_pk_mul_f32 v[28:29], v[28:29], v[42:43]
	s_nop 0
	v_add_f32_e32 v28, v29, v28
	v_cndmask_b32_e32 v25, v25, v28, vcc
	v_mul_f32_e32 v28, v150, v24
	v_mul_f32_e32 v29, v150, v25
	v_mov_b32_e32 v24, v30
	v_mov_b32_e32 v25, v26
	v_pk_mul_f32 v[24:25], v[24:25], v[32:33]
	s_nop 0
	v_sub_f32_e32 v24, v24, v25
	v_cndmask_b32_e32 v40, v30, v24, vcc
	v_mov_b32_e32 v24, v26
	v_mov_b32_e32 v25, v30
	v_pk_mul_f32 v[24:25], v[24:25], v[32:33]
	v_mov_b32_e32 v30, v27
	v_add_f32_e32 v24, v25, v24
	v_cndmask_b32_e32 v24, v26, v24, vcc
	v_mov_b32_e32 v26, v31
	v_mul_f32_e32 v33, v150, v24
	v_pk_mul_f32 v[24:25], v[26:27], v[34:35]
	v_mul_f32_e32 v32, v150, v40
	v_sub_f32_e32 v24, v24, v25
	v_cndmask_b32_e32 v26, v31, v24, vcc
	v_pk_mul_f32 v[24:25], v[30:31], v[34:35]
	s_nop 0
	v_add_f32_e32 v24, v25, v24
	v_cndmask_b32_e32 v24, v27, v24, vcc
	v_mul_f32_e32 v25, v150, v26
	v_mul_f32_e32 v27, v150, v24
	v_cvt_pk_bf16_f32 v24, v44, v28
	v_cvt_pk_bf16_f32 v25, v32, v25
	v_cvt_pk_bf16_f32 v26, v45, v29
	v_cvt_pk_bf16_f32 v27, v33, v27
; #define PG8_BAR __builtin_amdgcn_s_barrier()
;     __device__ __forceinline__ void operator()(const f32x4 (&acc)[2][2][4][2], const Unit& u, int wr, int wc, int fr_, int fq_) const {
;     ...
;         for (int ai = 0; ai < 2; ++ai)
; #pragma unroll
;             for (int m = 0; m < 4; ++m) {
;                 const int row = u.pm * BM + ai * HALF + wr * 64 + m * 16 + fr;
;                 const bool lat = row < tlat; const int s = row & 4095, prow = s >> 6, pcol = s & 63;
;                 bf16_t* rowp = base + (size_t)row * ld + colt + wc * 32 + 4 * fq;
; #pragma unroll
;                 for (int bj = 0; bj < 2; ++bj) {
;                     if (MODE == 0) {
;                         const int pos = (wc & 1) ? pcol : prow;
;                         const f32x4* tp = (const f32x4*)(tab + (size_t)(pos * 16 + 4 * fq) * 2);
;                         const f32x4 t0 = tp[0], t1 = tp[1];
;                         const f32x4 x1 = acc[ai][bj][m][0], x2 = acc[ai][bj][m][1];
;                         const float cs[4] = {t0[0], t0[2], t1[0], t1[2]}, sn[4] = {t0[1], t0[3], t1[1], t1[3]};
;                         float o1[4], o2[4];
; #pragma unroll
;                         for (int e = 0; e < 4; ++e) { o1[e] = lat ? x1[e] * cs[e] - x2[e] * sn[e] : x1[e]; o2[e] = lat ? x2[e] * cs[e] + x1[e] * sn[e] : x2[e]; o1[e] *= sc; o2[e] *= sc; }
;                         u32x2v w1, w2; w1.x = pk2e(o1[0], o1[1]); w1.y = pk2e(o1[2], o1[3]); w2.x = pk2e(o2[0], o2[1]); w2.y = pk2e(o2[2], o2[3]);
;                         *(u32x2v*)(rowp + bj * HALF) = w1; *(u32x2v*)(rowp + bj * HALF + 16) = w2;
; template <class Epi, class Sched, bool ALIGN_EPI = false, bool SP2 = false>
; __device__ __forceinline__ void gemm_phase(PG8_LAS unsigned char* lds, const Gemm g, const Sched& S, const Epi& E) {
;     ...
;         if constexpr (!Epi::AFTER_DRAIN) { E(acc, cur, wr, wc, fr, fq); S.done(cur); }
;         if (!has_next) break;
; #pragma unroll
;         for (int a = 0; a < 2; ++a)
; #pragma unroll
;             for (int b = 0; b < 2; ++b)
; #pragma unroll
;                 for (int m = 0; m < 4; ++m)
; #pragma unroll
;                     for (int n = 0; n < 2; ++n) acc[a][b][m][n] = (f32x4){0.f, 0.f, 0.f, 0.f};
;         cur = nxt; cA = nA; cB = nB; ++ui;
;         if constexpr (ALIGN_EPI) { if (wr == 1) PG8_BAR; }
	global_store_dwordx2 v[36:37], v[24:25], off
	global_store_dwordx2 v[36:37], v[26:27], off offset:32
	v_mov_b32_e32 v24, v164
	v_mov_b32_e32 v25, v165
	v_mov_b32_e32 v26, v166
	v_mov_b32_e32 v27, v167
	v_mov_b32_e32 v28, v168
	v_mov_b32_e32 v29, v169
	v_mov_b32_e32 v30, v170
	v_mov_b32_e32 v31, v171
	v_mov_b32_e32 v32, v20
	v_mov_b32_e32 v33, v16
	v_pk_mul_f32 v[32:33], v[32:33], v[28:29]
	s_nop 0
	v_sub_f32_e32 v32, v32, v33
	v_cndmask_b32_e32 v34, v20, v32, vcc
	v_mov_b32_e32 v32, v16
	v_mov_b32_e32 v33, v20
	v_pk_mul_f32 v[28:29], v[32:33], v[28:29]
	v_mul_f32_e32 v32, v150, v34
	v_add_f32_e32 v20, v29, v28
	v_cndmask_b32_e32 v16, v16, v20, vcc
	v_mul_f32_e32 v33, v150, v16
	v_mov_b32_e32 v16, v21
	v_pk_mul_f32 v[28:29], v[16:17], v[30:31]
	v_mov_b32_e32 v20, v17
	v_sub_f32_e32 v16, v28, v29
	v_cndmask_b32_e32 v16, v21, v16, vcc
	v_pk_mul_f32 v[20:21], v[20:21], v[30:31]
	v_mov_b32_e32 v29, v8
	v_add_f32_e32 v20, v21, v20
	v_cndmask_b32_e32 v17, v17, v20, vcc
	v_mul_f32_e32 v20, v150, v16
	v_mul_f32_e32 v21, v150, v17
	v_mov_b32_e32 v16, v22
	v_mov_b32_e32 v17, v18
	v_pk_mul_f32 v[16:17], v[16:17], v[24:25]
	s_nop 0
	v_sub_f32_e32 v16, v16, v17
	v_cndmask_b32_e32 v28, v22, v16, vcc
	v_mov_b32_e32 v16, v18
	v_mov_b32_e32 v17, v22
	v_pk_mul_f32 v[16:17], v[16:17], v[24:25]
	v_mov_b32_e32 v22, v19
	v_add_f32_e32 v16, v17, v16
	v_cndmask_b32_e32 v16, v18, v16, vcc
	v_mov_b32_e32 v18, v23
	v_mul_f32_e32 v25, v150, v16
	v_pk_mul_f32 v[16:17], v[18:19], v[26:27]
	v_mul_f32_e32 v24, v150, v28
	v_sub_f32_e32 v16, v16, v17
	v_cndmask_b32_e32 v18, v23, v16, vcc
	v_pk_mul_f32 v[16:17], v[22:23], v[26:27]
	v_mov_b32_e32 v28, v12
	v_add_f32_e32 v16, v17, v16
	v_cndmask_b32_e32 v16, v19, v16, vcc
	v_mul_f32_e32 v17, v150, v18
	v_mul_f32_e32 v19, v150, v16
	v_cvt_pk_bf16_f32 v16, v32, v20
	v_cvt_pk_bf16_f32 v17, v24, v17
	v_cvt_pk_bf16_f32 v18, v33, v21
	v_cvt_pk_bf16_f32 v19, v25, v19
	global_store_dwordx2 v[36:37], v[16:17], off offset:256
	global_store_dwordx2 v[36:37], v[18:19], off offset:288
	v_or_b32_e32 v16, s0, v88
	v_ashrrev_i32_e32 v17, 31, v16
	v_cmp_gt_i32_e32 vcc, s80, v16
	v_lshlrev_b64 v[16:17], 11, v[16:17]
	v_lshl_add_u64 v[20:21], v[142:143], 0, v[16:17]
	v_cndmask_b32_e64 v16, v88, v72, s[4:5]
	v_lshl_add_u32 v16, v16, 4, v140
	v_ashrrev_i32_e32 v17, 31, v16
	v_lshl_add_u64 v[22:23], v[16:17], 3, s[6:7]
	global_load_dwordx4 v[16:19], v[22:23], off offset:16
	global_load_dwordx4 v[24:27], v[22:23], off
	global_load_dwordx4 v[164:167], v[22:23], off offset:16
	global_load_dwordx4 v[168:171], v[22:23], off
	s_waitcnt vmcnt(0)
	v_pk_mul_f32 v[28:29], v[28:29], v[24:25]
	s_nop 0
	v_sub_f32_e32 v28, v28, v29
	v_cndmask_b32_e32 v30, v12, v28, vcc
	v_mov_b32_e32 v28, v8
	v_mov_b32_e32 v29, v12
	v_pk_mul_f32 v[24:25], v[28:29], v[24:25]
	v_mul_f32_e32 v28, v150, v30
	v_add_f32_e32 v12, v25, v24
	v_cndmask_b32_e32 v8, v8, v12, vcc
	v_mul_f32_e32 v29, v150, v8
	v_mov_b32_e32 v8, v13
	v_pk_mul_f32 v[24:25], v[8:9], v[26:27]
	v_mov_b32_e32 v12, v9
	v_sub_f32_e32 v8, v24, v25
	v_cndmask_b32_e32 v8, v13, v8, vcc
	v_pk_mul_f32 v[12:13], v[12:13], v[26:27]
	s_nop 0
	v_add_f32_e32 v12, v13, v12
	v_cndmask_b32_e32 v9, v9, v12, vcc
	v_mul_f32_e32 v12, v150, v8
	v_mul_f32_e32 v13, v150, v9
	v_mov_b32_e32 v8, v14
	v_mov_b32_e32 v9, v10
	v_pk_mul_f32 v[8:9], v[8:9], v[16:17]
	s_nop 0
	v_sub_f32_e32 v8, v8, v9
	v_cndmask_b32_e32 v24, v14, v8, vcc
	v_mov_b32_e32 v8, v10
	v_mov_b32_e32 v9, v14
	v_pk_mul_f32 v[8:9], v[8:9], v[16:17]
	v_mov_b32_e32 v14, v11
	v_add_f32_e32 v8, v9, v8
	v_cndmask_b32_e32 v8, v10, v8, vcc
	v_mov_b32_e32 v10, v15
	v_mul_f32_e32 v17, v150, v8
	v_pk_mul_f32 v[8:9], v[10:11], v[18:19]
	v_mul_f32_e32 v16, v150, v24
	v_sub_f32_e32 v8, v8, v9
	v_cndmask_b32_e32 v10, v15, v8, vcc
	v_pk_mul_f32 v[8:9], v[14:15], v[18:19]
	s_nop 0
	v_add_f32_e32 v8, v9, v8
	v_cndmask_b32_e32 v8, v11, v8, vcc
	v_mul_f32_e32 v9, v150, v10
	v_mul_f32_e32 v11, v150, v8
	v_cvt_pk_bf16_f32 v8, v28, v12
	v_cvt_pk_bf16_f32 v9, v16, v9
	v_cvt_pk_bf16_f32 v10, v29, v13
	v_cvt_pk_bf16_f32 v11, v17, v11
	global_store_dwordx2 v[20:21], v[8:9], off
	global_store_dwordx2 v[20:21], v[10:11], off offset:32
	v_mov_b32_e32 v8, v164
	v_mov_b32_e32 v9, v165
	v_mov_b32_e32 v10, v166
	v_mov_b32_e32 v11, v167
	v_mov_b32_e32 v12, v168
	v_mov_b32_e32 v13, v169
	v_mov_b32_e32 v14, v170
	v_mov_b32_e32 v15, v171
	v_mov_b32_e32 v16, v4
	v_mov_b32_e32 v17, v0
	v_pk_mul_f32 v[16:17], v[16:17], v[12:13]
	s_nop 0
	v_sub_f32_e32 v16, v16, v17
	v_cndmask_b32_e32 v18, v4, v16, vcc
	v_mov_b32_e32 v16, v0
	v_mov_b32_e32 v17, v4
	v_pk_mul_f32 v[12:13], v[16:17], v[12:13]
	s_nop 0
	v_add_f32_e32 v4, v13, v12
	v_cndmask_b32_e32 v16, v0, v4, vcc
	v_mov_b32_e32 v0, v5
	v_pk_mul_f32 v[12:13], v[0:1], v[14:15]
	v_mov_b32_e32 v4, v1
	v_sub_f32_e32 v0, v12, v13
	v_cndmask_b32_e32 v12, v5, v0, vcc
	v_pk_mul_f32 v[4:5], v[4:5], v[14:15]
	s_nop 0
	v_add_f32_e32 v0, v5, v4
	v_cndmask_b32_e32 v4, v1, v0, vcc
	v_mov_b32_e32 v0, v6
	v_mov_b32_e32 v1, v2
	v_pk_mul_f32 v[0:1], v[0:1], v[8:9]
	v_mul_f32_e32 v4, v150, v4
	v_sub_f32_e32 v0, v0, v1
	v_cndmask_b32_e32 v5, v6, v0, vcc
	v_mov_b32_e32 v0, v2
	v_mov_b32_e32 v1, v6
	v_pk_mul_f32 v[0:1], v[0:1], v[8:9]
	v_mov_b32_e32 v6, v3
	v_add_f32_e32 v0, v1, v0
	v_cndmask_b32_e32 v8, v2, v0, vcc
	v_mov_b32_e32 v2, v7
	v_pk_mul_f32 v[0:1], v[2:3], v[10:11]
	v_mul_f32_e32 v5, v150, v5
	v_sub_f32_e32 v0, v0, v1
	v_cndmask_b32_e32 v2, v7, v0, vcc
	v_pk_mul_f32 v[0:1], v[6:7], v[10:11]
	v_mul_f32_e32 v2, v150, v2
	v_add_f32_e32 v0, v1, v0
	v_cndmask_b32_e32 v0, v3, v0, vcc
	v_mul_f32_e32 v1, v150, v18
	v_mul_f32_e32 v3, v150, v12
	v_mul_f32_e32 v6, v150, v8
	v_mul_f32_e32 v7, v150, v16
	v_mul_f32_e32 v8, v150, v0
	v_cvt_pk_bf16_f32 v0, v1, v3
	v_cvt_pk_bf16_f32 v1, v5, v2
	s_andn2_b64 vcc, exec, s[88:89]
	v_cvt_pk_bf16_f32 v2, v7, v4
	v_cvt_pk_bf16_f32 v3, v6, v8
	global_store_dwordx2 v[20:21], v[0:1], off offset:256
	global_store_dwordx2 v[20:21], v[2:3], off offset:288
	s_cbranch_vccnz .LBB0_733
	s_andn2_b64 vcc, exec, s[8:9]
	s_cbranch_vccnz .LBB0_732
	s_barrier
	s_branch .LBB0_732

; __device__ __forceinline__ unsigned pk2e(float lo, float hi) { typedef float v2f __attribute__((ext_vector_type(2))); typedef __bf16 v2b __attribute__((ext_vector_type(2))); v2f v = {lo, hi}; v2b b = __builtin_convertvector(v, v2b); return __builtin_bit_cast(unsigned, b); }
;     __device__ __forceinline__ void operator()(const f32x4 (&acc)[2][2][4][2], const Unit& u, int wr, int wc, int fr_, int fq_) const {
;     ...
;         int colt = u.pn * BM; bf16_t* base = O0; int ld = ld0; float sc = qscale;
;         const int gcolt = colt;
;         if (split_col && colt >= split_col) { base = O1; ld = ld1; colt -= split_col; sc = 1.f; }
; #pragma unroll
;         for (int ai = 0; ai < 2; ++ai)
; #pragma unroll
;             for (int m = 0; m < 4; ++m) {
;                 const int row = u.pm * BM + ai * HALF + wr * 64 + m * 16 + fr;
;                 const bool lat = row < tlat; const int s = row & 4095, prow = s >> 6, pcol = s & 63;
;                 bf16_t* rowp = base + (size_t)row * ld + colt + wc * 32 + 4 * fq;
; #pragma unroll
;                 for (int bj = 0; bj < 2; ++bj) {
;                     if (MODE == 0) {
;                         const int pos = (wc & 1) ? pcol : prow;
;                         const f32x4* tp = (const f32x4*)(tab + (size_t)(pos * 16 + 4 * fq) * 2);
;                         const f32x4 t0 = tp[0], t1 = tp[1];
;                         const f32x4 x1 = acc[ai][bj][m][0], x2 = acc[ai][bj][m][1];
;                         const float cs[4] = {t0[0], t0[2], t1[0], t1[2]}, sn[4] = {t0[1], t0[3], t1[1], t1[3]};
;                         float o1[4], o2[4];
; #pragma unroll
;                         for (int e = 0; e < 4; ++e) { o1[e] = lat ? x1[e] * cs[e] - x2[e] * sn[e] : x1[e]; o2[e] = lat ? x2[e] * cs[e] + x1[e] * sn[e] : x2[e]; o1[e] *= sc; o2[e] *= sc; }
;                         u32x2v w1, w2; w1.x = pk2e(o1[0], o1[1]); w1.y = pk2e(o1[2], o1[3]); w2.x = pk2e(o2[0], o2[1]); w2.y = pk2e(o2[2], o2[3]);
;                         *(u32x2v*)(rowp + bj * HALF) = w1; *(u32x2v*)(rowp + bj * HALF + 16) = w2;
.LBB0_760:
	s_add_u32 s1, s6, s36
	s_addc_u32 s13, s7, s37
	s_ashr_i32 s35, s34, 31
	s_lshl_b64 s[2:3], s[34:35], 1
	s_add_u32 s1, s1, s2
	s_addc_u32 s3, s13, s3
	s_add_u32 s2, s1, s91
	v_and_b32_e32 v150, 15, v130
	s_addc_u32 s3, s3, 0
	v_ashrrev_i32_e32 v130, 2, v130
	s_lshl_b32 s1, s26, 8
	v_and_b32_e32 v140, -4, v130
	s_add_i32 s1, s1, s79
	v_ashrrev_i32_e32 v141, 31, v140
	v_or_b32_e32 v130, s1, v150
	s_bfe_u32 s13, s1, 0x60006
	v_lshl_add_u64 v[142:143], v[140:141], 1, s[2:3]
	v_cmp_gt_i32_e32 vcc, s80, v130
	v_mad_i64_i32 v[130:131], s[2:3], s28, v130, 0
	v_mov_b32_e32 v141, s13
	v_lshl_add_u64 v[144:145], v[130:131], 1, v[142:143]
	v_cndmask_b32_e64 v130, v150, v141, s[4:5]
	v_lshl_add_u32 v130, v130, 4, v140
	v_ashrrev_i32_e32 v131, 31, v130
	v_lshl_add_u64 v[146:147], v[130:131], 3, s[6:7]
	global_load_dwordx4 v[130:133], v[146:147], off offset:16
	global_load_dwordx4 v[152:155], v[146:147], off
	global_load_dwordx4 v[164:167], v[146:147], off offset:16
	global_load_dwordx4 v[168:171], v[146:147], off
	v_mov_b32_e32 v156, v126
	v_mov_b32_e32 v157, v122
	s_mov_b64 s[26:27], -1
	s_waitcnt vmcnt(0)
	v_pk_mul_f32 v[156:157], v[156:157], v[152:153]
	s_nop 0
	v_sub_f32_e32 v151, v156, v157
	v_mov_b32_e32 v156, v122
	v_mov_b32_e32 v157, v126
	v_pk_mul_f32 v[152:153], v[156:157], v[152:153]
	v_cndmask_b32_e32 v151, v126, v151, vcc
	v_add_f32_e32 v126, v153, v152
	v_cndmask_b32_e32 v122, v122, v126, vcc
	v_mul_f32_e32 v156, s0, v122
	v_mov_b32_e32 v122, v127
	v_pk_mul_f32 v[152:153], v[122:123], v[154:155]
	v_mov_b32_e32 v126, v123
	v_sub_f32_e32 v122, v152, v153
	v_cndmask_b32_e32 v122, v127, v122, vcc
	v_pk_mul_f32 v[126:127], v[126:127], v[154:155]
	v_mul_f32_e32 v151, s0, v151
	v_add_f32_e32 v126, v127, v126
	v_cndmask_b32_e32 v123, v123, v126, vcc
	v_mul_f32_e32 v126, s0, v122
	v_mul_f32_e32 v127, s0, v123
	v_mov_b32_e32 v122, v128
	v_mov_b32_e32 v123, v124
	v_pk_mul_f32 v[122:123], v[122:123], v[130:131]
	s_nop 0
	v_sub_f32_e32 v122, v122, v123
	v_cndmask_b32_e32 v152, v128, v122, vcc
	v_mov_b32_e32 v122, v124
	v_mov_b32_e32 v123, v128
	v_pk_mul_f32 v[122:123], v[122:123], v[130:131]
	v_mov_b32_e32 v128, v125
	v_add_f32_e32 v122, v123, v122
	v_cndmask_b32_e32 v122, v124, v122, vcc
	v_mov_b32_e32 v124, v129
	v_mul_f32_e32 v131, s0, v122
	v_pk_mul_f32 v[122:123], v[124:125], v[132:133]
	v_mul_f32_e32 v130, s0, v152
	v_sub_f32_e32 v122, v122, v123
	v_cndmask_b32_e32 v124, v129, v122, vcc
	v_pk_mul_f32 v[122:123], v[128:129], v[132:133]
	s_nop 0
	v_add_f32_e32 v122, v123, v122
	v_cndmask_b32_e32 v122, v125, v122, vcc
	v_mul_f32_e32 v123, s0, v124
	v_mul_f32_e32 v125, s0, v122
	v_cvt_pk_bf16_f32 v122, v151, v126
	v_cvt_pk_bf16_f32 v123, v130, v123
	v_cvt_pk_bf16_f32 v124, v156, v127
	v_cvt_pk_bf16_f32 v125, v131, v125
	global_store_dwordx2 v[144:145], v[122:123], off
	global_store_dwordx2 v[144:145], v[124:125], off offset:32
	v_mov_b32_e32 v122, v164
	v_mov_b32_e32 v123, v165
	v_mov_b32_e32 v124, v166
	v_mov_b32_e32 v125, v167
	v_mov_b32_e32 v126, v168
	v_mov_b32_e32 v127, v169
	v_mov_b32_e32 v128, v170
	v_mov_b32_e32 v129, v171
	v_mov_b32_e32 v130, v118
	v_mov_b32_e32 v131, v114
	v_pk_mul_f32 v[130:131], v[130:131], v[126:127]
	s_nop 0
	v_sub_f32_e32 v130, v130, v131
	v_cndmask_b32_e32 v132, v118, v130, vcc
	v_mov_b32_e32 v130, v114
	v_mov_b32_e32 v131, v118
	v_pk_mul_f32 v[126:127], v[130:131], v[126:127]
	v_mul_f32_e32 v130, s0, v132
	v_add_f32_e32 v118, v127, v126
	v_cndmask_b32_e32 v114, v114, v118, vcc
	v_mul_f32_e32 v131, s0, v114
	v_mov_b32_e32 v114, v119
	v_pk_mul_f32 v[126:127], v[114:115], v[128:129]
	v_mov_b32_e32 v118, v115
	v_sub_f32_e32 v114, v126, v127
	v_cndmask_b32_e32 v114, v119, v114, vcc
	v_pk_mul_f32 v[118:119], v[118:119], v[128:129]
	v_mov_b32_e32 v128, v108
	v_add_f32_e32 v118, v119, v118
	v_cndmask_b32_e32 v115, v115, v118, vcc
	v_mul_f32_e32 v118, s0, v114
	v_mul_f32_e32 v119, s0, v115
	v_mov_b32_e32 v114, v120
	v_mov_b32_e32 v115, v116
	v_pk_mul_f32 v[114:115], v[114:115], v[122:123]
	v_mov_b32_e32 v129, v104
	v_sub_f32_e32 v114, v114, v115
	v_cndmask_b32_e32 v126, v120, v114, vcc
	v_mov_b32_e32 v114, v116
	v_mov_b32_e32 v115, v120
	v_pk_mul_f32 v[114:115], v[114:115], v[122:123]
	v_mov_b32_e32 v120, v117
	v_add_f32_e32 v114, v115, v114
	v_cndmask_b32_e32 v114, v116, v114, vcc
	v_mov_b32_e32 v116, v121
	v_mul_f32_e32 v123, s0, v114
	v_pk_mul_f32 v[114:115], v[116:117], v[124:125]
	v_mul_f32_e32 v122, s0, v126
	v_sub_f32_e32 v114, v114, v115
	v_cndmask_b32_e32 v116, v121, v114, vcc
	v_pk_mul_f32 v[114:115], v[120:121], v[124:125]
	s_nop 0
	v_add_f32_e32 v114, v115, v114
	v_cndmask_b32_e32 v114, v117, v114, vcc
	v_mul_f32_e32 v115, s0, v116
	v_mul_f32_e32 v117, s0, v114
	v_cvt_pk_bf16_f32 v114, v130, v118
	v_cvt_pk_bf16_f32 v115, v122, v115
	v_or_b32_e32 v122, 16, v150
	v_cvt_pk_bf16_f32 v116, v131, v119
	v_cvt_pk_bf16_f32 v117, v123, v117
	global_store_dwordx2 v[144:145], v[114:115], off offset:256
	global_store_dwordx2 v[144:145], v[116:117], off offset:288
	v_or_b32_e32 v114, s1, v122
	v_cmp_gt_i32_e32 vcc, s80, v114
	v_mad_i64_i32 v[114:115], s[2:3], s28, v114, 0
	v_lshl_add_u64 v[118:119], v[114:115], 1, v[142:143]
	v_cndmask_b32_e64 v114, v122, v141, s[4:5]
	v_lshl_add_u32 v114, v114, 4, v140
	v_ashrrev_i32_e32 v115, 31, v114
	v_lshl_add_u64 v[120:121], v[114:115], 3, s[6:7]
	global_load_dwordx4 v[114:117], v[120:121], off offset:16
	global_load_dwordx4 v[124:127], v[120:121], off
	global_load_dwordx4 v[164:167], v[120:121], off offset:16
	global_load_dwordx4 v[168:171], v[120:121], off
	s_waitcnt vmcnt(0)
; __device__ __forceinline__ unsigned pk2e(float lo, float hi) { typedef float v2f __attribute__((ext_vector_type(2))); typedef __bf16 v2b __attribute__((ext_vector_type(2))); v2f v = {lo, hi}; v2b b = __builtin_convertvector(v, v2b); return __builtin_bit_cast(unsigned, b); }
;     __device__ __forceinline__ void operator()(const f32x4 (&acc)[2][2][4][2], const Unit& u, int wr, int wc, int fr_, int fq_) const {
;     ...
; #pragma unroll
;         for (int ai = 0; ai < 2; ++ai)
; #pragma unroll
;             for (int m = 0; m < 4; ++m) {
;                 const int row = u.pm * BM + ai * HALF + wr * 64 + m * 16 + fr;
;                 const bool lat = row < tlat; const int s = row & 4095, prow = s >> 6, pcol = s & 63;
;                 bf16_t* rowp = base + (size_t)row * ld + colt + wc * 32 + 4 * fq;
; #pragma unroll
;                 for (int bj = 0; bj < 2; ++bj) {
;                     if (MODE == 0) {
;                         const int pos = (wc & 1) ? pcol : prow;
;                         const f32x4* tp = (const f32x4*)(tab + (size_t)(pos * 16 + 4 * fq) * 2);
;                         const f32x4 t0 = tp[0], t1 = tp[1];
;                         const f32x4 x1 = acc[ai][bj][m][0], x2 = acc[ai][bj][m][1];
;                         const float cs[4] = {t0[0], t0[2], t1[0], t1[2]}, sn[4] = {t0[1], t0[3], t1[1], t1[3]};
;                         float o1[4], o2[4];
; #pragma unroll
;                         for (int e = 0; e < 4; ++e) { o1[e] = lat ? x1[e] * cs[e] - x2[e] * sn[e] : x1[e]; o2[e] = lat ? x2[e] * cs[e] + x1[e] * sn[e] : x2[e]; o1[e] *= sc; o2[e] *= sc; }
;                         u32x2v w1, w2; w1.x = pk2e(o1[0], o1[1]); w1.y = pk2e(o1[2], o1[3]); w2.x = pk2e(o2[0], o2[1]); w2.y = pk2e(o2[2], o2[3]);
;                         *(u32x2v*)(rowp + bj * HALF) = w1; *(u32x2v*)(rowp + bj * HALF + 16) = w2;
	v_pk_mul_f32 v[128:129], v[128:129], v[124:125]
	s_nop 0
	v_sub_f32_e32 v123, v128, v129
	v_mov_b32_e32 v128, v104
	v_mov_b32_e32 v129, v108
	v_pk_mul_f32 v[124:125], v[128:129], v[124:125]
	v_cndmask_b32_e32 v123, v108, v123, vcc
	v_add_f32_e32 v108, v125, v124
	v_cndmask_b32_e32 v104, v104, v108, vcc
	v_mul_f32_e32 v128, s0, v104
	v_mov_b32_e32 v104, v109
	v_pk_mul_f32 v[124:125], v[104:105], v[126:127]
	v_mov_b32_e32 v108, v105
	v_sub_f32_e32 v104, v124, v125
	v_cndmask_b32_e32 v104, v109, v104, vcc
	v_pk_mul_f32 v[108:109], v[108:109], v[126:127]
	v_mul_f32_e32 v123, s0, v123
	v_add_f32_e32 v108, v109, v108
	v_cndmask_b32_e32 v105, v105, v108, vcc
	v_mul_f32_e32 v108, s0, v104
	v_mul_f32_e32 v109, s0, v105
	v_mov_b32_e32 v104, v110
	v_mov_b32_e32 v105, v106
	v_pk_mul_f32 v[104:105], v[104:105], v[114:115]
	s_nop 0
	v_sub_f32_e32 v104, v104, v105
	v_cndmask_b32_e32 v124, v110, v104, vcc
	v_mov_b32_e32 v104, v106
	v_mov_b32_e32 v105, v110
	v_pk_mul_f32 v[104:105], v[104:105], v[114:115]
	v_mov_b32_e32 v110, v107
	v_add_f32_e32 v104, v105, v104
	v_cndmask_b32_e32 v104, v106, v104, vcc
	v_mov_b32_e32 v106, v111
	v_mul_f32_e32 v115, s0, v104
	v_pk_mul_f32 v[104:105], v[106:107], v[116:117]
	v_mul_f32_e32 v114, s0, v124
	v_sub_f32_e32 v104, v104, v105
	v_cndmask_b32_e32 v106, v111, v104, vcc
	v_pk_mul_f32 v[104:105], v[110:111], v[116:117]
	s_nop 0
	v_add_f32_e32 v104, v105, v104
	v_cndmask_b32_e32 v104, v107, v104, vcc
	v_mul_f32_e32 v105, s0, v106
	v_mul_f32_e32 v107, s0, v104
	v_cvt_pk_bf16_f32 v104, v123, v108
	v_cvt_pk_bf16_f32 v105, v114, v105
	v_cvt_pk_bf16_f32 v106, v128, v109
	v_cvt_pk_bf16_f32 v107, v115, v107
	global_store_dwordx2 v[118:119], v[104:105], off
	global_store_dwordx2 v[118:119], v[106:107], off offset:32
	v_mov_b32_e32 v104, v164
	v_mov_b32_e32 v105, v165
	v_mov_b32_e32 v106, v166
	v_mov_b32_e32 v107, v167
	v_mov_b32_e32 v108, v168
	v_mov_b32_e32 v109, v169
	v_mov_b32_e32 v110, v170
	v_mov_b32_e32 v111, v171
	v_mov_b32_e32 v114, v100
	v_mov_b32_e32 v115, v96
	v_pk_mul_f32 v[114:115], v[114:115], v[108:109]
	s_nop 0
	v_sub_f32_e32 v114, v114, v115
	v_cndmask_b32_e32 v116, v100, v114, vcc
	v_mov_b32_e32 v114, v96
	v_mov_b32_e32 v115, v100
	v_pk_mul_f32 v[108:109], v[114:115], v[108:109]
	v_mul_f32_e32 v114, s0, v116
	v_add_f32_e32 v100, v109, v108
	v_cndmask_b32_e32 v96, v96, v100, vcc
	v_mul_f32_e32 v115, s0, v96
	v_mov_b32_e32 v96, v101
	v_pk_mul_f32 v[108:109], v[96:97], v[110:111]
	v_mov_b32_e32 v100, v97
	v_sub_f32_e32 v96, v108, v109
	v_cndmask_b32_e32 v96, v101, v96, vcc
	v_pk_mul_f32 v[100:101], v[100:101], v[110:111]
	v_mov_b32_e32 v110, v92
	v_add_f32_e32 v100, v101, v100
	v_cndmask_b32_e32 v97, v97, v100, vcc
	v_mul_f32_e32 v100, s0, v96
	v_mul_f32_e32 v101, s0, v97
	v_mov_b32_e32 v96, v102
	v_mov_b32_e32 v97, v98
	v_pk_mul_f32 v[96:97], v[96:97], v[104:105]
	v_mov_b32_e32 v111, v88
	v_sub_f32_e32 v96, v96, v97
	v_cndmask_b32_e32 v108, v102, v96, vcc
	v_mov_b32_e32 v96, v98
	v_mov_b32_e32 v97, v102
	v_pk_mul_f32 v[96:97], v[96:97], v[104:105]
	v_mov_b32_e32 v102, v99
	v_add_f32_e32 v96, v97, v96
	v_cndmask_b32_e32 v96, v98, v96, vcc
	v_mov_b32_e32 v98, v103
	v_mul_f32_e32 v105, s0, v96
	v_pk_mul_f32 v[96:97], v[98:99], v[106:107]
	v_mul_f32_e32 v104, s0, v108
	v_sub_f32_e32 v96, v96, v97
	v_cndmask_b32_e32 v98, v103, v96, vcc
	v_pk_mul_f32 v[96:97], v[102:103], v[106:107]
	s_nop 0
	v_add_f32_e32 v96, v97, v96
	v_cndmask_b32_e32 v96, v99, v96, vcc
	v_mul_f32_e32 v97, s0, v98
	v_mul_f32_e32 v99, s0, v96
	v_cvt_pk_bf16_f32 v96, v114, v100
	v_cvt_pk_bf16_f32 v97, v104, v97
	v_or_b32_e32 v104, 32, v150
	v_cvt_pk_bf16_f32 v98, v115, v101
	v_cvt_pk_bf16_f32 v99, v105, v99
	global_store_dwordx2 v[118:119], v[96:97], off offset:256
	global_store_dwordx2 v[118:119], v[98:99], off offset:288
	v_or_b32_e32 v96, s1, v104
	v_cmp_gt_i32_e32 vcc, s80, v96
	v_mad_i64_i32 v[96:97], s[2:3], s28, v96, 0
	v_lshl_add_u64 v[100:101], v[96:97], 1, v[142:143]
	v_cndmask_b32_e64 v96, v104, v141, s[4:5]
	v_lshl_add_u32 v96, v96, 4, v140
	v_ashrrev_i32_e32 v97, 31, v96
	v_lshl_add_u64 v[102:103], v[96:97], 3, s[6:7]
	global_load_dwordx4 v[96:99], v[102:103], off offset:16
	global_load_dwordx4 v[106:109], v[102:103], off
	global_load_dwordx4 v[164:167], v[102:103], off offset:16
	global_load_dwordx4 v[168:171], v[102:103], off
	s_waitcnt vmcnt(0)
; __device__ __forceinline__ unsigned pk2e(float lo, float hi) { typedef float v2f __attribute__((ext_vector_type(2))); typedef __bf16 v2b __attribute__((ext_vector_type(2))); v2f v = {lo, hi}; v2b b = __builtin_convertvector(v, v2b); return __builtin_bit_cast(unsigned, b); }
;     __device__ __forceinline__ void operator()(const f32x4 (&acc)[2][2][4][2], const Unit& u, int wr, int wc, int fr_, int fq_) const {
;     ...
; #pragma unroll
;         for (int ai = 0; ai < 2; ++ai)
; #pragma unroll
;             for (int m = 0; m < 4; ++m) {
;                 const int row = u.pm * BM + ai * HALF + wr * 64 + m * 16 + fr;
;                 const bool lat = row < tlat; const int s = row & 4095, prow = s >> 6, pcol = s & 63;
;                 bf16_t* rowp = base + (size_t)row * ld + colt + wc * 32 + 4 * fq;
; #pragma unroll
;                 for (int bj = 0; bj < 2; ++bj) {
;                     if (MODE == 0) {
;                         const int pos = (wc & 1) ? pcol : prow;
;                         const f32x4* tp = (const f32x4*)(tab + (size_t)(pos * 16 + 4 * fq) * 2);
;                         const f32x4 t0 = tp[0], t1 = tp[1];
;                         const f32x4 x1 = acc[ai][bj][m][0], x2 = acc[ai][bj][m][1];
;                         const float cs[4] = {t0[0], t0[2], t1[0], t1[2]}, sn[4] = {t0[1], t0[3], t1[1], t1[3]};
;                         float o1[4], o2[4];
; #pragma unroll
;                         for (int e = 0; e < 4; ++e) { o1[e] = lat ? x1[e] * cs[e] - x2[e] * sn[e] : x1[e]; o2[e] = lat ? x2[e] * cs[e] + x1[e] * sn[e] : x2[e]; o1[e] *= sc; o2[e] *= sc; }
;                         u32x2v w1, w2; w1.x = pk2e(o1[0], o1[1]); w1.y = pk2e(o1[2], o1[3]); w2.x = pk2e(o2[0], o2[1]); w2.y = pk2e(o2[2], o2[3]);
;                         *(u32x2v*)(rowp + bj * HALF) = w1; *(u32x2v*)(rowp + bj * HALF + 16) = w2;
	v_pk_mul_f32 v[110:111], v[110:111], v[106:107]
	s_nop 0
	v_sub_f32_e32 v105, v110, v111
	v_mov_b32_e32 v110, v88
	v_mov_b32_e32 v111, v92
	v_pk_mul_f32 v[106:107], v[110:111], v[106:107]
	v_cndmask_b32_e32 v105, v92, v105, vcc
	v_add_f32_e32 v92, v107, v106
	v_cndmask_b32_e32 v88, v88, v92, vcc
	v_mul_f32_e32 v110, s0, v88
	v_mov_b32_e32 v88, v93
	v_pk_mul_f32 v[106:107], v[88:89], v[108:109]
	v_mov_b32_e32 v92, v89
	v_sub_f32_e32 v88, v106, v107
	v_cndmask_b32_e32 v88, v93, v88, vcc
	v_pk_mul_f32 v[92:93], v[92:93], v[108:109]
	v_mul_f32_e32 v105, s0, v105
	v_add_f32_e32 v92, v93, v92
	v_cndmask_b32_e32 v89, v89, v92, vcc
	v_mul_f32_e32 v92, s0, v88
	v_mul_f32_e32 v93, s0, v89
	v_mov_b32_e32 v88, v94
	v_mov_b32_e32 v89, v90
	v_pk_mul_f32 v[88:89], v[88:89], v[96:97]
	s_nop 0
	v_sub_f32_e32 v88, v88, v89
	v_cndmask_b32_e32 v106, v94, v88, vcc
	v_mov_b32_e32 v88, v90
	v_mov_b32_e32 v89, v94
	v_pk_mul_f32 v[88:89], v[88:89], v[96:97]
	v_mov_b32_e32 v94, v91
	v_add_f32_e32 v88, v89, v88
	v_cndmask_b32_e32 v88, v90, v88, vcc
	v_mov_b32_e32 v90, v95
	v_mul_f32_e32 v97, s0, v88
	v_pk_mul_f32 v[88:89], v[90:91], v[98:99]
	v_mul_f32_e32 v96, s0, v106
	v_sub_f32_e32 v88, v88, v89
	v_cndmask_b32_e32 v90, v95, v88, vcc
	v_pk_mul_f32 v[88:89], v[94:95], v[98:99]
	s_nop 0
	v_add_f32_e32 v88, v89, v88
	v_cndmask_b32_e32 v88, v91, v88, vcc
	v_mul_f32_e32 v89, s0, v90
	v_mul_f32_e32 v91, s0, v88
	v_cvt_pk_bf16_f32 v88, v105, v92
	v_cvt_pk_bf16_f32 v89, v96, v89
	v_cvt_pk_bf16_f32 v90, v110, v93
	v_cvt_pk_bf16_f32 v91, v97, v91
	global_store_dwordx2 v[100:101], v[88:89], off
	global_store_dwordx2 v[100:101], v[90:91], off offset:32
	v_mov_b32_e32 v88, v164
	v_mov_b32_e32 v89, v165
	v_mov_b32_e32 v90, v166
	v_mov_b32_e32 v91, v167
	v_mov_b32_e32 v92, v168
	v_mov_b32_e32 v93, v169
	v_mov_b32_e32 v94, v170
	v_mov_b32_e32 v95, v171
	v_mov_b32_e32 v96, v84
	v_mov_b32_e32 v97, v80
	v_pk_mul_f32 v[96:97], v[96:97], v[92:93]
	s_nop 0
	v_sub_f32_e32 v96, v96, v97
	v_cndmask_b32_e32 v98, v84, v96, vcc
	v_mov_b32_e32 v96, v80
	v_mov_b32_e32 v97, v84
	v_pk_mul_f32 v[92:93], v[96:97], v[92:93]
	v_mul_f32_e32 v96, s0, v98
	v_add_f32_e32 v84, v93, v92
	v_cndmask_b32_e32 v80, v80, v84, vcc
	v_mul_f32_e32 v97, s0, v80
	v_mov_b32_e32 v80, v85
	v_pk_mul_f32 v[92:93], v[80:81], v[94:95]
	v_mov_b32_e32 v84, v81
	v_sub_f32_e32 v80, v92, v93
	v_cndmask_b32_e32 v80, v85, v80, vcc
	v_pk_mul_f32 v[84:85], v[84:85], v[94:95]
	v_mov_b32_e32 v94, v76
	v_add_f32_e32 v84, v85, v84
	v_cndmask_b32_e32 v81, v81, v84, vcc
	v_mul_f32_e32 v84, s0, v80
	v_mul_f32_e32 v85, s0, v81
	v_mov_b32_e32 v80, v86
	v_mov_b32_e32 v81, v82
	v_pk_mul_f32 v[80:81], v[80:81], v[88:89]
	v_mov_b32_e32 v95, v72
	v_sub_f32_e32 v80, v80, v81
	v_cndmask_b32_e32 v92, v86, v80, vcc
	v_mov_b32_e32 v80, v82
	v_mov_b32_e32 v81, v86
	v_pk_mul_f32 v[80:81], v[80:81], v[88:89]
	v_mov_b32_e32 v86, v83
	v_add_f32_e32 v80, v81, v80
	v_cndmask_b32_e32 v80, v82, v80, vcc
	v_mov_b32_e32 v82, v87
	v_mul_f32_e32 v89, s0, v80
	v_pk_mul_f32 v[80:81], v[82:83], v[90:91]
	v_mul_f32_e32 v88, s0, v92
	v_sub_f32_e32 v80, v80, v81
	v_cndmask_b32_e32 v82, v87, v80, vcc
	v_pk_mul_f32 v[80:81], v[86:87], v[90:91]
	s_nop 0
	v_add_f32_e32 v80, v81, v80
	v_cndmask_b32_e32 v80, v83, v80, vcc
	v_mul_f32_e32 v81, s0, v82
	v_mul_f32_e32 v83, s0, v80
	v_cvt_pk_bf16_f32 v80, v96, v84
	v_cvt_pk_bf16_f32 v81, v88, v81
	v_or_b32_e32 v88, 48, v150
	v_cvt_pk_bf16_f32 v82, v97, v85
	v_cvt_pk_bf16_f32 v83, v89, v83
	global_store_dwordx2 v[100:101], v[80:81], off offset:256
	global_store_dwordx2 v[100:101], v[82:83], off offset:288
	v_or_b32_e32 v80, s1, v88
	v_cmp_gt_i32_e32 vcc, s80, v80
	v_mad_i64_i32 v[80:81], s[2:3], s28, v80, 0
	v_lshl_add_u64 v[84:85], v[80:81], 1, v[142:143]
	v_cndmask_b32_e64 v80, v88, v141, s[4:5]
	v_lshl_add_u32 v80, v80, 4, v140
	v_ashrrev_i32_e32 v81, 31, v80
	v_lshl_add_u64 v[86:87], v[80:81], 3, s[6:7]
	global_load_dwordx4 v[80:83], v[86:87], off offset:16
	global_load_dwordx4 v[90:93], v[86:87], off
	global_load_dwordx4 v[164:167], v[86:87], off offset:16
	global_load_dwordx4 v[168:171], v[86:87], off
	s_addk_i32 s1, 0x80
	s_bfe_u32 s13, s1, 0x60006
	s_waitcnt vmcnt(0)
	v_pk_mul_f32 v[94:95], v[94:95], v[90:91]
	s_nop 0
	v_sub_f32_e32 v89, v94, v95
	v_mov_b32_e32 v94, v72
	v_mov_b32_e32 v95, v76
	v_pk_mul_f32 v[90:91], v[94:95], v[90:91]
	v_cndmask_b32_e32 v89, v76, v89, vcc
	v_add_f32_e32 v76, v91, v90
	v_cndmask_b32_e32 v72, v72, v76, vcc
	v_mul_f32_e32 v94, s0, v72
	v_mov_b32_e32 v72, v77
	v_pk_mul_f32 v[90:91], v[72:73], v[92:93]
	v_mov_b32_e32 v76, v73
	v_sub_f32_e32 v72, v90, v91
	v_cndmask_b32_e32 v72, v77, v72, vcc
	v_pk_mul_f32 v[76:77], v[76:77], v[92:93]
	v_mul_f32_e32 v89, s0, v89
	v_add_f32_e32 v76, v77, v76
	v_cndmask_b32_e32 v73, v73, v76, vcc
	v_mul_f32_e32 v76, s0, v72
	v_mul_f32_e32 v77, s0, v73
	v_mov_b32_e32 v72, v78
	v_mov_b32_e32 v73, v74
	v_pk_mul_f32 v[72:73], v[72:73], v[80:81]
	s_nop 0
	v_sub_f32_e32 v72, v72, v73
	v_cndmask_b32_e32 v90, v78, v72, vcc
	v_mov_b32_e32 v72, v74
	v_mov_b32_e32 v73, v78
	v_pk_mul_f32 v[72:73], v[72:73], v[80:81]
	v_mov_b32_e32 v78, v75
	v_add_f32_e32 v72, v73, v72
	v_cndmask_b32_e32 v72, v74, v72, vcc
	v_mov_b32_e32 v74, v79
	v_mul_f32_e32 v81, s0, v72
	v_pk_mul_f32 v[72:73], v[74:75], v[82:83]
	v_mul_f32_e32 v80, s0, v90
	v_sub_f32_e32 v72, v72, v73
	v_cndmask_b32_e32 v74, v79, v72, vcc
	v_pk_mul_f32 v[72:73], v[78:79], v[82:83]
	s_nop 0
	v_add_f32_e32 v72, v73, v72
	v_cndmask_b32_e32 v72, v75, v72, vcc
	v_mul_f32_e32 v73, s0, v74
	v_mul_f32_e32 v75, s0, v72
	v_cvt_pk_bf16_f32 v72, v89, v76
	v_cvt_pk_bf16_f32 v73, v80, v73
	v_cvt_pk_bf16_f32 v74, v94, v77
; __device__ __forceinline__ unsigned pk2e(float lo, float hi) { typedef float v2f __attribute__((ext_vector_type(2))); typedef __bf16 v2b __attribute__((ext_vector_type(2))); v2f v = {lo, hi}; v2b b = __builtin_convertvector(v, v2b); return __builtin_bit_cast(unsigned, b); }
;     __device__ __forceinline__ void operator()(const f32x4 (&acc)[2][2][4][2], const Unit& u, int wr, int wc, int fr_, int fq_) const {
;     ...
; #pragma unroll
;         for (int ai = 0; ai < 2; ++ai)
; #pragma unroll
;             for (int m = 0; m < 4; ++m) {
;                 const int row = u.pm * BM + ai * HALF + wr * 64 + m * 16 + fr;
;                 const bool lat = row < tlat; const int s = row & 4095, prow = s >> 6, pcol = s & 63;
;                 bf16_t* rowp = base + (size_t)row * ld + colt + wc * 32 + 4 * fq;
; #pragma unroll
;                 for (int bj = 0; bj < 2; ++bj) {
;                     if (MODE == 0) {
;                         const int pos = (wc & 1) ? pcol : prow;
;                         const f32x4* tp = (const f32x4*)(tab + (size_t)(pos * 16 + 4 * fq) * 2);
;                         const f32x4 t0 = tp[0], t1 = tp[1];
;                         const f32x4 x1 = acc[ai][bj][m][0], x2 = acc[ai][bj][m][1];
;                         const float cs[4] = {t0[0], t0[2], t1[0], t1[2]}, sn[4] = {t0[1], t0[3], t1[1], t1[3]};
;                         float o1[4], o2[4];
; #pragma unroll
;                         for (int e = 0; e < 4; ++e) { o1[e] = lat ? x1[e] * cs[e] - x2[e] * sn[e] : x1[e]; o2[e] = lat ? x2[e] * cs[e] + x1[e] * sn[e] : x2[e]; o1[e] *= sc; o2[e] *= sc; }
;                         u32x2v w1, w2; w1.x = pk2e(o1[0], o1[1]); w1.y = pk2e(o1[2], o1[3]); w2.x = pk2e(o2[0], o2[1]); w2.y = pk2e(o2[2], o2[3]);
;                         *(u32x2v*)(rowp + bj * HALF) = w1; *(u32x2v*)(rowp + bj * HALF + 16) = w2;
	v_cvt_pk_bf16_f32 v75, v81, v75
	global_store_dwordx2 v[84:85], v[72:73], off
	global_store_dwordx2 v[84:85], v[74:75], off offset:32
	v_mov_b32_e32 v72, v164
	v_mov_b32_e32 v73, v165
	v_mov_b32_e32 v74, v166
	v_mov_b32_e32 v75, v167
	v_mov_b32_e32 v76, v168
	v_mov_b32_e32 v77, v169
	v_mov_b32_e32 v78, v170
	v_mov_b32_e32 v79, v171
	v_mov_b32_e32 v80, v68
	v_mov_b32_e32 v81, v64
	v_pk_mul_f32 v[80:81], v[80:81], v[76:77]
	s_nop 0
	v_sub_f32_e32 v80, v80, v81
	v_cndmask_b32_e32 v82, v68, v80, vcc
	v_mov_b32_e32 v80, v64
	v_mov_b32_e32 v81, v68
	v_pk_mul_f32 v[76:77], v[80:81], v[76:77]
	v_mul_f32_e32 v80, s0, v82
	v_add_f32_e32 v68, v77, v76
	v_cndmask_b32_e32 v64, v64, v68, vcc
	v_mul_f32_e32 v81, s0, v64
	v_mov_b32_e32 v64, v69
	v_pk_mul_f32 v[76:77], v[64:65], v[78:79]
	v_mov_b32_e32 v68, v65
	v_sub_f32_e32 v64, v76, v77
	v_cndmask_b32_e32 v64, v69, v64, vcc
	v_pk_mul_f32 v[68:69], v[68:69], v[78:79]
	v_mov_b32_e32 v78, v60
	v_add_f32_e32 v68, v69, v68
	v_cndmask_b32_e32 v65, v65, v68, vcc
	v_mul_f32_e32 v68, s0, v64
	v_mul_f32_e32 v69, s0, v65
	v_mov_b32_e32 v64, v70
	v_mov_b32_e32 v65, v66
	v_pk_mul_f32 v[64:65], v[64:65], v[72:73]
	v_mov_b32_e32 v79, v56
	v_sub_f32_e32 v64, v64, v65
	v_cndmask_b32_e32 v76, v70, v64, vcc
	v_mov_b32_e32 v64, v66
	v_mov_b32_e32 v65, v70
	v_pk_mul_f32 v[64:65], v[64:65], v[72:73]
	v_mov_b32_e32 v70, v67
	v_add_f32_e32 v64, v65, v64
	v_cndmask_b32_e32 v64, v66, v64, vcc
	v_mov_b32_e32 v66, v71
	v_mul_f32_e32 v73, s0, v64
	v_pk_mul_f32 v[64:65], v[66:67], v[74:75]
	v_mul_f32_e32 v72, s0, v76
	v_sub_f32_e32 v64, v64, v65
	v_cndmask_b32_e32 v66, v71, v64, vcc
	v_pk_mul_f32 v[64:65], v[70:71], v[74:75]
	s_nop 0
	v_add_f32_e32 v64, v65, v64
	v_cndmask_b32_e32 v64, v67, v64, vcc
	v_mul_f32_e32 v65, s0, v66
	v_mul_f32_e32 v67, s0, v64
	v_cvt_pk_bf16_f32 v64, v80, v68
	v_cvt_pk_bf16_f32 v65, v72, v65
	v_cvt_pk_bf16_f32 v66, v81, v69
	v_cvt_pk_bf16_f32 v67, v73, v67
	global_store_dwordx2 v[84:85], v[64:65], off offset:256
	global_store_dwordx2 v[84:85], v[66:67], off offset:288
	v_or_b32_e32 v64, s1, v150
	v_cmp_gt_i32_e32 vcc, s80, v64
	v_mad_i64_i32 v[64:65], s[2:3], s28, v64, 0
	v_mov_b32_e32 v72, s13
	v_lshl_add_u64 v[68:69], v[64:65], 1, v[142:143]
	v_cndmask_b32_e64 v64, v150, v72, s[4:5]
	v_lshl_add_u32 v64, v64, 4, v140
	v_ashrrev_i32_e32 v65, 31, v64
	v_lshl_add_u64 v[70:71], v[64:65], 3, s[6:7]
	global_load_dwordx4 v[64:67], v[70:71], off offset:16
	global_load_dwordx4 v[74:77], v[70:71], off
	global_load_dwordx4 v[164:167], v[70:71], off offset:16
	global_load_dwordx4 v[168:171], v[70:71], off
	s_waitcnt vmcnt(0)
	v_pk_mul_f32 v[78:79], v[78:79], v[74:75]
	s_nop 0
	v_sub_f32_e32 v73, v78, v79
	v_mov_b32_e32 v78, v56
	v_mov_b32_e32 v79, v60
	v_pk_mul_f32 v[74:75], v[78:79], v[74:75]
	v_cndmask_b32_e32 v73, v60, v73, vcc
	v_add_f32_e32 v60, v75, v74
	v_cndmask_b32_e32 v56, v56, v60, vcc
	v_mul_f32_e32 v78, s0, v56
	v_mov_b32_e32 v56, v61
	v_pk_mul_f32 v[74:75], v[56:57], v[76:77]
	v_mov_b32_e32 v60, v57
	v_sub_f32_e32 v56, v74, v75
	v_cndmask_b32_e32 v56, v61, v56, vcc
	v_pk_mul_f32 v[60:61], v[60:61], v[76:77]
	v_mul_f32_e32 v73, s0, v73
	v_add_f32_e32 v60, v61, v60
	v_cndmask_b32_e32 v57, v57, v60, vcc
	v_mul_f32_e32 v60, s0, v56
	v_mul_f32_e32 v61, s0, v57
	v_mov_b32_e32 v56, v62
	v_mov_b32_e32 v57, v58
	v_pk_mul_f32 v[56:57], v[56:57], v[64:65]
	s_nop 0
	v_sub_f32_e32 v56, v56, v57
	v_cndmask_b32_e32 v74, v62, v56, vcc
	v_mov_b32_e32 v56, v58
	v_mov_b32_e32 v57, v62
	v_pk_mul_f32 v[56:57], v[56:57], v[64:65]
	v_mov_b32_e32 v62, v59
	v_add_f32_e32 v56, v57, v56
	v_cndmask_b32_e32 v56, v58, v56, vcc
	v_mov_b32_e32 v58, v63
	v_mul_f32_e32 v65, s0, v56
	v_pk_mul_f32 v[56:57], v[58:59], v[66:67]
	v_mul_f32_e32 v64, s0, v74
	v_sub_f32_e32 v56, v56, v57
	v_cndmask_b32_e32 v58, v63, v56, vcc
	v_pk_mul_f32 v[56:57], v[62:63], v[66:67]
	s_nop 0
	v_add_f32_e32 v56, v57, v56
	v_cndmask_b32_e32 v56, v59, v56, vcc
	v_mul_f32_e32 v57, s0, v58
	v_mul_f32_e32 v59, s0, v56
	v_cvt_pk_bf16_f32 v56, v73, v60
	v_cvt_pk_bf16_f32 v57, v64, v57
	v_cvt_pk_bf16_f32 v58, v78, v61
	v_cvt_pk_bf16_f32 v59, v65, v59
	global_store_dwordx2 v[68:69], v[56:57], off
	global_store_dwordx2 v[68:69], v[58:59], off offset:32
	v_mov_b32_e32 v56, v164
	v_mov_b32_e32 v57, v165
	v_mov_b32_e32 v58, v166
	v_mov_b32_e32 v59, v167
	v_mov_b32_e32 v60, v168
	v_mov_b32_e32 v61, v169
	v_mov_b32_e32 v62, v170
	v_mov_b32_e32 v63, v171
	v_mov_b32_e32 v64, v52
	v_mov_b32_e32 v65, v48
	v_pk_mul_f32 v[64:65], v[64:65], v[60:61]
	s_nop 0
	v_sub_f32_e32 v64, v64, v65
	v_cndmask_b32_e32 v66, v52, v64, vcc
	v_mov_b32_e32 v64, v48
	v_mov_b32_e32 v65, v52
	v_pk_mul_f32 v[60:61], v[64:65], v[60:61]
	v_mul_f32_e32 v64, s0, v66
	v_add_f32_e32 v52, v61, v60
	v_cndmask_b32_e32 v48, v48, v52, vcc
	v_mul_f32_e32 v65, s0, v48
	v_mov_b32_e32 v48, v53
	v_pk_mul_f32 v[60:61], v[48:49], v[62:63]
	v_mov_b32_e32 v52, v49
	v_sub_f32_e32 v48, v60, v61
	v_cndmask_b32_e32 v48, v53, v48, vcc
	v_pk_mul_f32 v[52:53], v[52:53], v[62:63]
	v_mov_b32_e32 v61, v40
	v_add_f32_e32 v52, v53, v52
	v_cndmask_b32_e32 v49, v49, v52, vcc
	v_mul_f32_e32 v52, s0, v48
	v_mul_f32_e32 v53, s0, v49
	v_mov_b32_e32 v48, v54
	v_mov_b32_e32 v49, v50
	v_pk_mul_f32 v[48:49], v[48:49], v[56:57]
	s_nop 0
	v_sub_f32_e32 v48, v48, v49
	v_cndmask_b32_e32 v60, v54, v48, vcc
	v_mov_b32_e32 v48, v50
	v_mov_b32_e32 v49, v54
	v_pk_mul_f32 v[48:49], v[48:49], v[56:57]
	v_mov_b32_e32 v54, v51
	v_add_f32_e32 v48, v49, v48
	v_cndmask_b32_e32 v48, v50, v48, vcc
	v_mov_b32_e32 v50, v55
	v_mul_f32_e32 v57, s0, v48
	v_pk_mul_f32 v[48:49], v[50:51], v[58:59]
	v_mul_f32_e32 v56, s0, v60
	v_sub_f32_e32 v48, v48, v49
	v_cndmask_b32_e32 v50, v55, v48, vcc
	v_pk_mul_f32 v[48:49], v[54:55], v[58:59]
	v_mov_b32_e32 v60, v44
	v_add_f32_e32 v48, v49, v48
	v_cndmask_b32_e32 v48, v51, v48, vcc
	v_mul_f32_e32 v49, s0, v50
	v_mul_f32_e32 v51, s0, v48
	v_cvt_pk_bf16_f32 v48, v64, v52
	v_cvt_pk_bf16_f32 v49, v56, v49
	v_cvt_pk_bf16_f32 v50, v65, v53
	v_cvt_pk_bf16_f32 v51, v57, v51
	global_store_dwordx2 v[68:69], v[48:49], off offset:256
	global_store_dwordx2 v[68:69], v[50:51], off offset:288
	v_or_b32_e32 v48, s1, v122
	v_cmp_gt_i32_e32 vcc, s80, v48
	v_mad_i64_i32 v[48:49], s[2:3], s28, v48, 0
	v_lshl_add_u64 v[52:53], v[48:49], 1, v[142:143]
	v_cndmask_b32_e64 v48, v122, v72, s[4:5]
	v_lshl_add_u32 v48, v48, 4, v140
	v_ashrrev_i32_e32 v49, 31, v48
	v_lshl_add_u64 v[54:55], v[48:49], 3, s[6:7]
	global_load_dwordx4 v[48:51], v[54:55], off offset:16
	global_load_dwordx4 v[56:59], v[54:55], off
	global_load_dwordx4 v[164:167], v[54:55], off offset:16
	global_load_dwordx4 v[168:171], v[54:55], off
	s_waitcnt vmcnt(0)
; __device__ __forceinline__ unsigned pk2e(float lo, float hi) { typedef float v2f __attribute__((ext_vector_type(2))); typedef __bf16 v2b __attribute__((ext_vector_type(2))); v2f v = {lo, hi}; v2b b = __builtin_convertvector(v, v2b); return __builtin_bit_cast(unsigned, b); }
;     __device__ __forceinline__ void operator()(const f32x4 (&acc)[2][2][4][2], const Unit& u, int wr, int wc, int fr_, int fq_) const {
;     ...
; #pragma unroll
;         for (int ai = 0; ai < 2; ++ai)
; #pragma unroll
;             for (int m = 0; m < 4; ++m) {
;                 const int row = u.pm * BM + ai * HALF + wr * 64 + m * 16 + fr;
;                 const bool lat = row < tlat; const int s = row & 4095, prow = s >> 6, pcol = s & 63;
;                 bf16_t* rowp = base + (size_t)row * ld + colt + wc * 32 + 4 * fq;
; #pragma unroll
;                 for (int bj = 0; bj < 2; ++bj) {
;                     if (MODE == 0) {
;                         const int pos = (wc & 1) ? pcol : prow;
;                         const f32x4* tp = (const f32x4*)(tab + (size_t)(pos * 16 + 4 * fq) * 2);
;                         const f32x4 t0 = tp[0], t1 = tp[1];
;                         const f32x4 x1 = acc[ai][bj][m][0], x2 = acc[ai][bj][m][1];
;                         const float cs[4] = {t0[0], t0[2], t1[0], t1[2]}, sn[4] = {t0[1], t0[3], t1[1], t1[3]};
;                         float o1[4], o2[4];
; #pragma unroll
;                         for (int e = 0; e < 4; ++e) { o1[e] = lat ? x1[e] * cs[e] - x2[e] * sn[e] : x1[e]; o2[e] = lat ? x2[e] * cs[e] + x1[e] * sn[e] : x2[e]; o1[e] *= sc; o2[e] *= sc; }
;                         u32x2v w1, w2; w1.x = pk2e(o1[0], o1[1]); w1.y = pk2e(o1[2], o1[3]); w2.x = pk2e(o2[0], o2[1]); w2.y = pk2e(o2[2], o2[3]);
;                         *(u32x2v*)(rowp + bj * HALF) = w1; *(u32x2v*)(rowp + bj * HALF + 16) = w2;
	v_pk_mul_f32 v[60:61], v[60:61], v[56:57]
	s_nop 0
	v_sub_f32_e32 v60, v60, v61
	v_cndmask_b32_e32 v62, v44, v60, vcc
	v_mov_b32_e32 v60, v40
	v_mov_b32_e32 v61, v44
	v_pk_mul_f32 v[56:57], v[60:61], v[56:57]
	v_mul_f32_e32 v60, s0, v62
	v_add_f32_e32 v44, v57, v56
	v_cndmask_b32_e32 v40, v40, v44, vcc
	v_mul_f32_e32 v61, s0, v40
	v_mov_b32_e32 v40, v45
	v_pk_mul_f32 v[56:57], v[40:41], v[58:59]
	v_mov_b32_e32 v44, v41
	v_sub_f32_e32 v40, v56, v57
	v_cndmask_b32_e32 v40, v45, v40, vcc
	v_pk_mul_f32 v[44:45], v[44:45], v[58:59]
	s_nop 0
	v_add_f32_e32 v44, v45, v44
	v_cndmask_b32_e32 v41, v41, v44, vcc
	v_mul_f32_e32 v44, s0, v40
	v_mul_f32_e32 v45, s0, v41
	v_mov_b32_e32 v40, v46
	v_mov_b32_e32 v41, v42
	v_pk_mul_f32 v[40:41], v[40:41], v[48:49]
	s_nop 0
	v_sub_f32_e32 v40, v40, v41
	v_cndmask_b32_e32 v56, v46, v40, vcc
	v_mov_b32_e32 v40, v42
	v_mov_b32_e32 v41, v46
	v_pk_mul_f32 v[40:41], v[40:41], v[48:49]
	v_mov_b32_e32 v46, v43
	v_add_f32_e32 v40, v41, v40
	v_cndmask_b32_e32 v40, v42, v40, vcc
	v_mov_b32_e32 v42, v47
	v_mul_f32_e32 v49, s0, v40
	v_pk_mul_f32 v[40:41], v[42:43], v[50:51]
	v_mul_f32_e32 v48, s0, v56
	v_sub_f32_e32 v40, v40, v41
	v_cndmask_b32_e32 v42, v47, v40, vcc
	v_pk_mul_f32 v[40:41], v[46:47], v[50:51]
	s_nop 0
	v_add_f32_e32 v40, v41, v40
	v_cndmask_b32_e32 v40, v43, v40, vcc
	v_mul_f32_e32 v41, s0, v42
	v_mul_f32_e32 v43, s0, v40
	v_cvt_pk_bf16_f32 v40, v60, v44
	v_cvt_pk_bf16_f32 v41, v48, v41
	v_cvt_pk_bf16_f32 v42, v61, v45
	v_cvt_pk_bf16_f32 v43, v49, v43
	global_store_dwordx2 v[52:53], v[40:41], off
	global_store_dwordx2 v[52:53], v[42:43], off offset:32
	v_mov_b32_e32 v40, v164
	v_mov_b32_e32 v41, v165
	v_mov_b32_e32 v42, v166
	v_mov_b32_e32 v43, v167
	v_mov_b32_e32 v44, v168
	v_mov_b32_e32 v45, v169
	v_mov_b32_e32 v46, v170
	v_mov_b32_e32 v47, v171
	v_mov_b32_e32 v48, v36
	v_mov_b32_e32 v49, v32
	v_pk_mul_f32 v[48:49], v[48:49], v[44:45]
	s_nop 0
	v_sub_f32_e32 v48, v48, v49
	v_cndmask_b32_e32 v50, v36, v48, vcc
	v_mov_b32_e32 v48, v32
	v_mov_b32_e32 v49, v36
	v_pk_mul_f32 v[44:45], v[48:49], v[44:45]
	v_mul_f32_e32 v48, s0, v50
	v_add_f32_e32 v36, v45, v44
	v_cndmask_b32_e32 v32, v32, v36, vcc
	v_mul_f32_e32 v49, s0, v32
	v_mov_b32_e32 v32, v37
	v_pk_mul_f32 v[44:45], v[32:33], v[46:47]
	v_mov_b32_e32 v36, v33
	v_sub_f32_e32 v32, v44, v45
	v_cndmask_b32_e32 v32, v37, v32, vcc
	v_pk_mul_f32 v[36:37], v[36:37], v[46:47]
	v_mov_b32_e32 v45, v24
	v_add_f32_e32 v36, v37, v36
	v_cndmask_b32_e32 v33, v33, v36, vcc
	v_mul_f32_e32 v36, s0, v32
	v_mul_f32_e32 v37, s0, v33
	v_mov_b32_e32 v32, v38
	v_mov_b32_e32 v33, v34
	v_pk_mul_f32 v[32:33], v[32:33], v[40:41]
	s_nop 0
	v_sub_f32_e32 v32, v32, v33
	v_cndmask_b32_e32 v44, v38, v32, vcc
	v_mov_b32_e32 v32, v34
	v_mov_b32_e32 v33, v38
	v_pk_mul_f32 v[32:33], v[32:33], v[40:41]
	v_mov_b32_e32 v38, v35
	v_add_f32_e32 v32, v33, v32
	v_cndmask_b32_e32 v32, v34, v32, vcc
	v_mov_b32_e32 v34, v39
	v_mul_f32_e32 v41, s0, v32
	v_pk_mul_f32 v[32:33], v[34:35], v[42:43]
	v_mul_f32_e32 v40, s0, v44
	v_sub_f32_e32 v32, v32, v33
	v_cndmask_b32_e32 v34, v39, v32, vcc
	v_pk_mul_f32 v[32:33], v[38:39], v[42:43]
	v_mov_b32_e32 v44, v28
	v_add_f32_e32 v32, v33, v32
	v_cndmask_b32_e32 v32, v35, v32, vcc
	v_mul_f32_e32 v33, s0, v34
	v_mul_f32_e32 v35, s0, v32
	v_cvt_pk_bf16_f32 v32, v48, v36
	v_cvt_pk_bf16_f32 v33, v40, v33
	v_cvt_pk_bf16_f32 v34, v49, v37
	v_cvt_pk_bf16_f32 v35, v41, v35
	global_store_dwordx2 v[52:53], v[32:33], off offset:256
	global_store_dwordx2 v[52:53], v[34:35], off offset:288
	v_or_b32_e32 v32, s1, v104
	v_cmp_gt_i32_e32 vcc, s80, v32
	v_mad_i64_i32 v[32:33], s[2:3], s28, v32, 0
	v_lshl_add_u64 v[36:37], v[32:33], 1, v[142:143]
	v_cndmask_b32_e64 v32, v104, v72, s[4:5]
	v_lshl_add_u32 v32, v32, 4, v140
	v_ashrrev_i32_e32 v33, 31, v32
	v_lshl_add_u64 v[38:39], v[32:33], 3, s[6:7]
	global_load_dwordx4 v[32:35], v[38:39], off offset:16
	global_load_dwordx4 v[40:43], v[38:39], off
	global_load_dwordx4 v[164:167], v[38:39], off offset:16
	global_load_dwordx4 v[168:171], v[38:39], off
	s_waitcnt vmcnt(0)
	v_pk_mul_f32 v[44:45], v[44:45], v[40:41]
	s_nop 0
	v_sub_f32_e32 v44, v44, v45
	v_cndmask_b32_e32 v46, v28, v44, vcc
	v_mov_b32_e32 v44, v24
	v_mov_b32_e32 v45, v28
	v_pk_mul_f32 v[40:41], v[44:45], v[40:41]
	v_mul_f32_e32 v44, s0, v46
	v_add_f32_e32 v28, v41, v40
	v_cndmask_b32_e32 v24, v24, v28, vcc
	v_mul_f32_e32 v45, s0, v24
	v_mov_b32_e32 v24, v29
	v_pk_mul_f32 v[40:41], v[24:25], v[42:43]
	v_mov_b32_e32 v28, v25
	v_sub_f32_e32 v24, v40, v41
	v_cndmask_b32_e32 v24, v29, v24, vcc
	v_pk_mul_f32 v[28:29], v[28:29], v[42:43]
	s_nop 0
	v_add_f32_e32 v28, v29, v28
	v_cndmask_b32_e32 v25, v25, v28, vcc
	v_mul_f32_e32 v28, s0, v24
	v_mul_f32_e32 v29, s0, v25
	v_mov_b32_e32 v24, v30
	v_mov_b32_e32 v25, v26
	v_pk_mul_f32 v[24:25], v[24:25], v[32:33]
	s_nop 0
	v_sub_f32_e32 v24, v24, v25
	v_cndmask_b32_e32 v40, v30, v24, vcc
	v_mov_b32_e32 v24, v26
	v_mov_b32_e32 v25, v30
	v_pk_mul_f32 v[24:25], v[24:25], v[32:33]
	v_mov_b32_e32 v30, v27
	v_add_f32_e32 v24, v25, v24
	v_cndmask_b32_e32 v24, v26, v24, vcc
	v_mov_b32_e32 v26, v31
	v_mul_f32_e32 v33, s0, v24
	v_pk_mul_f32 v[24:25], v[26:27], v[34:35]
	v_mul_f32_e32 v32, s0, v40
	v_sub_f32_e32 v24, v24, v25
	v_cndmask_b32_e32 v26, v31, v24, vcc
	v_pk_mul_f32 v[24:25], v[30:31], v[34:35]
	s_nop 0
	v_add_f32_e32 v24, v25, v24
	v_cndmask_b32_e32 v24, v27, v24, vcc
	v_mul_f32_e32 v25, s0, v26
	v_mul_f32_e32 v27, s0, v24
	v_cvt_pk_bf16_f32 v24, v44, v28
	v_cvt_pk_bf16_f32 v25, v32, v25
	v_cvt_pk_bf16_f32 v26, v45, v29
	v_cvt_pk_bf16_f32 v27, v33, v27
	global_store_dwordx2 v[36:37], v[24:25], off
	global_store_dwordx2 v[36:37], v[26:27], off offset:32
; #define PG8_BAR __builtin_amdgcn_s_barrier()
;     __device__ __forceinline__ void operator()(const f32x4 (&acc)[2][2][4][2], const Unit& u, int wr, int wc, int fr_, int fq_) const {
;     ...
;         for (int ai = 0; ai < 2; ++ai)
; #pragma unroll
;             for (int m = 0; m < 4; ++m) {
;                 const int row = u.pm * BM + ai * HALF + wr * 64 + m * 16 + fr;
;                 const bool lat = row < tlat; const int s = row & 4095, prow = s >> 6, pcol = s & 63;
;                 bf16_t* rowp = base + (size_t)row * ld + colt + wc * 32 + 4 * fq;
; #pragma unroll
;                 for (int bj = 0; bj < 2; ++bj) {
;                     if (MODE == 0) {
;                         const int pos = (wc & 1) ? pcol : prow;
;                         const f32x4* tp = (const f32x4*)(tab + (size_t)(pos * 16 + 4 * fq) * 2);
;                         const f32x4 t0 = tp[0], t1 = tp[1];
;                         const f32x4 x1 = acc[ai][bj][m][0], x2 = acc[ai][bj][m][1];
;                         const float cs[4] = {t0[0], t0[2], t1[0], t1[2]}, sn[4] = {t0[1], t0[3], t1[1], t1[3]};
;                         float o1[4], o2[4];
; #pragma unroll
;                         for (int e = 0; e < 4; ++e) { o1[e] = lat ? x1[e] * cs[e] - x2[e] * sn[e] : x1[e]; o2[e] = lat ? x2[e] * cs[e] + x1[e] * sn[e] : x2[e]; o1[e] *= sc; o2[e] *= sc; }
;                         u32x2v w1, w2; w1.x = pk2e(o1[0], o1[1]); w1.y = pk2e(o1[2], o1[3]); w2.x = pk2e(o2[0], o2[1]); w2.y = pk2e(o2[2], o2[3]);
;                         *(u32x2v*)(rowp + bj * HALF) = w1; *(u32x2v*)(rowp + bj * HALF + 16) = w2;
; template <class Epi, class Sched, bool ALIGN_EPI = false, bool SP2 = false>
; __device__ __forceinline__ void gemm_phase(PG8_LAS unsigned char* lds, const Gemm g, const Sched& S, const Epi& E) {
;     ...
;         if constexpr (!Epi::AFTER_DRAIN) { E(acc, cur, wr, wc, fr, fq); S.done(cur); }
;         if (!has_next) break;
; #pragma unroll
;         for (int a = 0; a < 2; ++a)
; #pragma unroll
;             for (int b = 0; b < 2; ++b)
; #pragma unroll
;                 for (int m = 0; m < 4; ++m)
; #pragma unroll
;                     for (int n = 0; n < 2; ++n) acc[a][b][m][n] = (f32x4){0.f, 0.f, 0.f, 0.f};
;         cur = nxt; cA = nA; cB = nB; ++ui;
;         if constexpr (ALIGN_EPI) { if (wr == 1) PG8_BAR; }
	v_mov_b32_e32 v24, v164
	v_mov_b32_e32 v25, v165
	v_mov_b32_e32 v26, v166
	v_mov_b32_e32 v27, v167
	v_mov_b32_e32 v28, v168
	v_mov_b32_e32 v29, v169
	v_mov_b32_e32 v30, v170
	v_mov_b32_e32 v31, v171
	v_mov_b32_e32 v32, v20
	v_mov_b32_e32 v33, v16
	v_pk_mul_f32 v[32:33], v[32:33], v[28:29]
	s_nop 0
	v_sub_f32_e32 v32, v32, v33
	v_cndmask_b32_e32 v34, v20, v32, vcc
	v_mov_b32_e32 v32, v16
	v_mov_b32_e32 v33, v20
	v_pk_mul_f32 v[28:29], v[32:33], v[28:29]
	v_mul_f32_e32 v32, s0, v34
	v_add_f32_e32 v20, v29, v28
	v_cndmask_b32_e32 v16, v16, v20, vcc
	v_mul_f32_e32 v33, s0, v16
	v_mov_b32_e32 v16, v21
	v_pk_mul_f32 v[28:29], v[16:17], v[30:31]
	v_mov_b32_e32 v20, v17
	v_sub_f32_e32 v16, v28, v29
	v_cndmask_b32_e32 v16, v21, v16, vcc
	v_pk_mul_f32 v[20:21], v[20:21], v[30:31]
	v_mov_b32_e32 v29, v8
	v_add_f32_e32 v20, v21, v20
	v_cndmask_b32_e32 v17, v17, v20, vcc
	v_mul_f32_e32 v20, s0, v16
	v_mul_f32_e32 v21, s0, v17
	v_mov_b32_e32 v16, v22
	v_mov_b32_e32 v17, v18
	v_pk_mul_f32 v[16:17], v[16:17], v[24:25]
	s_nop 0
	v_sub_f32_e32 v16, v16, v17
	v_cndmask_b32_e32 v28, v22, v16, vcc
	v_mov_b32_e32 v16, v18
	v_mov_b32_e32 v17, v22
	v_pk_mul_f32 v[16:17], v[16:17], v[24:25]
	v_mov_b32_e32 v22, v19
	v_add_f32_e32 v16, v17, v16
	v_cndmask_b32_e32 v16, v18, v16, vcc
	v_mov_b32_e32 v18, v23
	v_mul_f32_e32 v25, s0, v16
	v_pk_mul_f32 v[16:17], v[18:19], v[26:27]
	v_mul_f32_e32 v24, s0, v28
	v_sub_f32_e32 v16, v16, v17
	v_cndmask_b32_e32 v18, v23, v16, vcc
	v_pk_mul_f32 v[16:17], v[22:23], v[26:27]
	v_mov_b32_e32 v28, v12
	v_add_f32_e32 v16, v17, v16
	v_cndmask_b32_e32 v16, v19, v16, vcc
	v_mul_f32_e32 v17, s0, v18
	v_mul_f32_e32 v19, s0, v16
	v_cvt_pk_bf16_f32 v16, v32, v20
	v_cvt_pk_bf16_f32 v17, v24, v17
	v_cvt_pk_bf16_f32 v18, v33, v21
	v_cvt_pk_bf16_f32 v19, v25, v19
	global_store_dwordx2 v[36:37], v[16:17], off offset:256
	global_store_dwordx2 v[36:37], v[18:19], off offset:288
	v_or_b32_e32 v16, s1, v88
	v_cmp_gt_i32_e32 vcc, s80, v16
	v_mad_i64_i32 v[16:17], s[2:3], s28, v16, 0
	v_lshl_add_u64 v[20:21], v[16:17], 1, v[142:143]
	v_cndmask_b32_e64 v16, v88, v72, s[4:5]
	v_lshl_add_u32 v16, v16, 4, v140
	v_ashrrev_i32_e32 v17, 31, v16
	v_lshl_add_u64 v[22:23], v[16:17], 3, s[6:7]
	global_load_dwordx4 v[16:19], v[22:23], off offset:16
	global_load_dwordx4 v[24:27], v[22:23], off
	global_load_dwordx4 v[164:167], v[22:23], off offset:16
	global_load_dwordx4 v[168:171], v[22:23], off
	s_waitcnt vmcnt(0)
	v_pk_mul_f32 v[28:29], v[28:29], v[24:25]
	s_nop 0
	v_sub_f32_e32 v28, v28, v29
	v_cndmask_b32_e32 v30, v12, v28, vcc
	v_mov_b32_e32 v28, v8
	v_mov_b32_e32 v29, v12
	v_pk_mul_f32 v[24:25], v[28:29], v[24:25]
	v_mul_f32_e32 v28, s0, v30
	v_add_f32_e32 v12, v25, v24
	v_cndmask_b32_e32 v8, v8, v12, vcc
	v_mul_f32_e32 v29, s0, v8
	v_mov_b32_e32 v8, v13
	v_pk_mul_f32 v[24:25], v[8:9], v[26:27]
	v_mov_b32_e32 v12, v9
	v_sub_f32_e32 v8, v24, v25
	v_cndmask_b32_e32 v8, v13, v8, vcc
	v_pk_mul_f32 v[12:13], v[12:13], v[26:27]
	s_nop 0
	v_add_f32_e32 v12, v13, v12
	v_cndmask_b32_e32 v9, v9, v12, vcc
	v_mul_f32_e32 v12, s0, v8
	v_mul_f32_e32 v13, s0, v9
	v_mov_b32_e32 v8, v14
	v_mov_b32_e32 v9, v10
	v_pk_mul_f32 v[8:9], v[8:9], v[16:17]
	s_nop 0
	v_sub_f32_e32 v8, v8, v9
	v_cndmask_b32_e32 v24, v14, v8, vcc
	v_mov_b32_e32 v8, v10
	v_mov_b32_e32 v9, v14
	v_pk_mul_f32 v[8:9], v[8:9], v[16:17]
	v_mov_b32_e32 v14, v11
	v_add_f32_e32 v8, v9, v8
	v_cndmask_b32_e32 v8, v10, v8, vcc
	v_mov_b32_e32 v10, v15
	v_mul_f32_e32 v17, s0, v8
	v_pk_mul_f32 v[8:9], v[10:11], v[18:19]
	v_mul_f32_e32 v16, s0, v24
	v_sub_f32_e32 v8, v8, v9
	v_cndmask_b32_e32 v10, v15, v8, vcc
	v_pk_mul_f32 v[8:9], v[14:15], v[18:19]
	s_nop 0
	v_add_f32_e32 v8, v9, v8
	v_cndmask_b32_e32 v8, v11, v8, vcc
	v_mul_f32_e32 v9, s0, v10
	v_mul_f32_e32 v11, s0, v8
	v_cvt_pk_bf16_f32 v8, v28, v12
	v_cvt_pk_bf16_f32 v9, v16, v9
	v_cvt_pk_bf16_f32 v10, v29, v13
	v_cvt_pk_bf16_f32 v11, v17, v11
	global_store_dwordx2 v[20:21], v[8:9], off
	global_store_dwordx2 v[20:21], v[10:11], off offset:32
	v_mov_b32_e32 v8, v164
	v_mov_b32_e32 v9, v165
	v_mov_b32_e32 v10, v166
	v_mov_b32_e32 v11, v167
	v_mov_b32_e32 v12, v168
	v_mov_b32_e32 v13, v169
	v_mov_b32_e32 v14, v170
	v_mov_b32_e32 v15, v171
	v_mov_b32_e32 v16, v4
	v_mov_b32_e32 v17, v0
	v_pk_mul_f32 v[16:17], v[16:17], v[12:13]
	s_nop 0
	v_sub_f32_e32 v16, v16, v17
	v_cndmask_b32_e32 v18, v4, v16, vcc
	v_mov_b32_e32 v16, v0
	v_mov_b32_e32 v17, v4
	v_pk_mul_f32 v[12:13], v[16:17], v[12:13]
	s_nop 0
	v_add_f32_e32 v4, v13, v12
	v_cndmask_b32_e32 v16, v0, v4, vcc
	v_mov_b32_e32 v0, v5
	v_pk_mul_f32 v[12:13], v[0:1], v[14:15]
	v_mov_b32_e32 v4, v1
	v_sub_f32_e32 v0, v12, v13
	v_cndmask_b32_e32 v12, v5, v0, vcc
	v_pk_mul_f32 v[4:5], v[4:5], v[14:15]
	s_nop 0
	v_add_f32_e32 v0, v5, v4
	v_cndmask_b32_e32 v4, v1, v0, vcc
	v_mov_b32_e32 v0, v6
	v_mov_b32_e32 v1, v2
	v_pk_mul_f32 v[0:1], v[0:1], v[8:9]
	v_mul_f32_e32 v4, s0, v4
	v_sub_f32_e32 v0, v0, v1
	v_cndmask_b32_e32 v5, v6, v0, vcc
	v_mov_b32_e32 v0, v2
	v_mov_b32_e32 v1, v6
	v_pk_mul_f32 v[0:1], v[0:1], v[8:9]
	v_mov_b32_e32 v6, v3
	v_add_f32_e32 v0, v1, v0
	v_cndmask_b32_e32 v8, v2, v0, vcc
	v_mov_b32_e32 v2, v7
	v_pk_mul_f32 v[0:1], v[2:3], v[10:11]
	v_mul_f32_e32 v5, s0, v5
	v_sub_f32_e32 v0, v0, v1
	v_cndmask_b32_e32 v2, v7, v0, vcc
	v_pk_mul_f32 v[0:1], v[6:7], v[10:11]
	v_mul_f32_e32 v2, s0, v2
	v_add_f32_e32 v0, v1, v0
	v_cndmask_b32_e32 v0, v3, v0, vcc
	v_mul_f32_e32 v1, s0, v18
	v_mul_f32_e32 v3, s0, v12
	v_mul_f32_e32 v6, s0, v8
	v_mul_f32_e32 v7, s0, v16
	v_mul_f32_e32 v8, s0, v0
	v_cvt_pk_bf16_f32 v0, v1, v3
	v_cvt_pk_bf16_f32 v1, v5, v2
	s_andn2_b64 vcc, exec, s[88:89]
	v_cvt_pk_bf16_f32 v2, v7, v4
	v_cvt_pk_bf16_f32 v3, v6, v8
	global_store_dwordx2 v[20:21], v[0:1], off offset:256
	global_store_dwordx2 v[20:21], v[2:3], off offset:288
	s_cbranch_vccnz .LBB0_750
	s_andn2_b64 vcc, exec, s[8:9]
	s_cbranch_vccnz .LBB0_749
	s_barrier
	s_branch .LBB0_749
